# GEMM loops: LDS fragment reads moved from load segments into MFMA segments (interleaved), extra vmcnt(8) waits
# speedup vs baseline: 1.0084x; 1.0084x over previous
; #define PG8_STAGE(bufoff, gbase, voff) do { _Pragma("unroll") for (int _i = 0; _i < 2; ++_i) \
;     __builtin_amdgcn_global_load_lds((const unsigned*)((const char*)(gbase) + (voff)[_i]), (LAS unsigned*)(lds + (bufoff) + ldsw + _i * 8192), 16, 0, 0); } while (0)
; #define PG8_LDA(dst, b, h) do { _Pragma("unroll") for (int m = 0; m < 4; ++m) _Pragma("unroll") for (int k = 0; k < 2; ++k) dst[m][k] = *(const LAS bf16x8*)(lds + PG8_SA(b, h) + aoff + m * 2048 + k * 1024); } while (0)
; #define PG8_LDB(dst, b, h) do { _Pragma("unroll") for (int n = 0; n < 2; ++n) _Pragma("unroll") for (int k = 0; k < 2; ++k) dst[n][k] = *(const LAS bf16x8*)(lds + PG8_SB(b, h) + boff + n * 2048 + k * 1024); } while (0)
; #define PG8_MMA(ai, bj, At, Bt) do { __builtin_amdgcn_s_setprio(1); _Pragma("unroll") for (int m = 0; m < 4; ++m) _Pragma("unroll") for (int n = 0; n < 2; ++n) _Pragma("unroll") for (int k = 0; k < 2; ++k) \
;     acc[ai][bj][m][n] = __builtin_amdgcn_mfma_f32_16x16x32_bf16(Bt[n][k], At[m][k], acc[ai][bj][m][n], 0, 0, 0); __builtin_amdgcn_s_setprio(0); } while (0)
; #define PG8_WAIT_L(n) asm volatile("s_waitcnt lgkmcnt(" #n ")" ::: "memory")
; #define PG8_BAR __builtin_amdgcn_s_barrier()
; #define PG8_SCHED __builtin_amdgcn_sched_barrier(0)
; template <class Epi>
; DI void gemm_phase(LAS unsigned char* lds, const Gemm g, const Epi& E) {
;     ...
;     const bool has_next = S.next(ui + 1, nxt);
;     const char* nA = has_next ? PG8_APTR(nxt) : cA; const char* nB = has_next ? (const char*)g.Bt + (size_t)nxt.pn * tstepB : cB;
;     for (int t = 0; t < nt; t += 2) {
;       const bool last = (t == nt - 2);
;       const char* a1 = cA + (size_t)(t + 1) * kstep;
;       const char* a2 = last ? nA : cA + (size_t)(t + 2) * kstep; const char* b2 = last ? nB : cB + (size_t)(t + 2) * kstep;
;       const char* a3 = a2 + kstep; const char* b3 = b2 + kstep;
;       PG8_LDB(B0, 0, 0); PG8_SCHED; PG8_LDA(At, 0, 0); PG8_STAGE(PG8_SA(1, 1), a1 + hstepA, voffA);
;       PG8_WAIT_L(8); PG8_BAR; PG8_WAIT_L(0); PG8_MMA(0, 0, At, B0); PG8_BAR; PG8_SCHED;
;     ...
; #pragma unroll
;     for (int a = 0; a < 2; ++a)
; #pragma unroll
;       for (int b = 0; b < 2; ++b)
; #pragma unroll
;         for (int m = 0; m < 4; ++m)
; #pragma unroll
;           for (int n = 0; n < 2; ++n) acc[a][b][m][n] = (f32x4){0.f, 0.f, 0.f, 0.f};
;     cur = nxt; cA = nA; cB = nB; ++ui;
.LBB0_189:
	s_ashr_i32 s13, s12, 31
	v_cmp_lt_i64_e32 vcc, s[18:19], v[170:171]
	s_lshl_b64 s[18:19], s[12:13], 20
	s_add_u32 s18, s42, s18
	s_addc_u32 s19, s43, s19
	s_and_b64 s[22:23], vcc, exec
	s_cselect_b32 s13, s19, s31
	s_cselect_b32 s55, s18, s30
	s_ashr_i32 s3, s2, 31
	s_lshl_b64 s[22:23], s[2:3], 20
	s_add_u32 s22, s44, s22
	s_addc_u32 s23, s45, s23
	s_and_b64 s[40:41], vcc, exec
	s_cselect_b32 s3, s23, s37
	s_cselect_b32 s56, s22, s36
	s_add_u32 s30, s30, 0x80080
	s_addc_u32 s31, s31, 0
	s_add_u32 s57, s36, 0x100
	v_mov_b32_e32 v4, 0
	s_addc_u32 s58, s37, 0
	s_mov_b32 s59, -2
	v_mov_b32_e32 v5, v4
	v_mov_b32_e32 v6, v4
	v_mov_b32_e32 v7, v4
	v_mov_b32_e32 v12, v4
	v_mov_b32_e32 v13, v4
	v_mov_b32_e32 v14, v4
	v_mov_b32_e32 v15, v4
	v_mov_b32_e32 v20, v4
	v_mov_b32_e32 v21, v4
	v_mov_b32_e32 v22, v4
	v_mov_b32_e32 v23, v4
	v_mov_b32_e32 v28, v4
	v_mov_b32_e32 v29, v4
	v_mov_b32_e32 v30, v4
	v_mov_b32_e32 v31, v4
	v_mov_b32_e32 v36, v4
	v_mov_b32_e32 v37, v4
	v_mov_b32_e32 v38, v4
	v_mov_b32_e32 v39, v4
	v_mov_b32_e32 v44, v4
	v_mov_b32_e32 v45, v4
	v_mov_b32_e32 v46, v4
	v_mov_b32_e32 v47, v4
	v_mov_b32_e32 v52, v4
	v_mov_b32_e32 v53, v4
	v_mov_b32_e32 v54, v4
	v_mov_b32_e32 v55, v4
	v_mov_b32_e32 v60, v4
	v_mov_b32_e32 v61, v4
	v_mov_b32_e32 v62, v4
	v_mov_b32_e32 v63, v4
	v_mov_b32_e32 v8, v4
	v_mov_b32_e32 v9, v4
	v_mov_b32_e32 v10, v4
	v_mov_b32_e32 v11, v4
	v_mov_b32_e32 v16, v4
	v_mov_b32_e32 v17, v4
	v_mov_b32_e32 v18, v4
	v_mov_b32_e32 v19, v4
	v_mov_b32_e32 v24, v4
	v_mov_b32_e32 v25, v4
	v_mov_b32_e32 v26, v4
	v_mov_b32_e32 v27, v4
	v_mov_b32_e32 v32, v4
	v_mov_b32_e32 v33, v4
	v_mov_b32_e32 v34, v4
	v_mov_b32_e32 v35, v4
	v_mov_b32_e32 v40, v4
	v_mov_b32_e32 v41, v4
	v_mov_b32_e32 v42, v4
	v_mov_b32_e32 v43, v4
	v_mov_b32_e32 v48, v4
	v_mov_b32_e32 v49, v4
	v_mov_b32_e32 v50, v4
	v_mov_b32_e32 v51, v4
	v_mov_b32_e32 v56, v4
	v_mov_b32_e32 v57, v4
	v_mov_b32_e32 v58, v4
	v_mov_b32_e32 v59, v4
	v_mov_b32_e32 v64, v4
	v_mov_b32_e32 v65, v4
	v_mov_b32_e32 v66, v4
	v_mov_b32_e32 v67, v4
	v_mov_b32_e32 v68, v4
	v_mov_b32_e32 v69, v4
	v_mov_b32_e32 v70, v4
	v_mov_b32_e32 v71, v4
	v_mov_b32_e32 v76, v4
	v_mov_b32_e32 v77, v4
	v_mov_b32_e32 v78, v4
	v_mov_b32_e32 v79, v4
	v_mov_b32_e32 v84, v4
	v_mov_b32_e32 v85, v4
	v_mov_b32_e32 v86, v4
	v_mov_b32_e32 v87, v4
	v_mov_b32_e32 v92, v4
	v_mov_b32_e32 v93, v4
	v_mov_b32_e32 v94, v4
	v_mov_b32_e32 v95, v4
	v_mov_b32_e32 v100, v4
	v_mov_b32_e32 v101, v4
	v_mov_b32_e32 v102, v4
	v_mov_b32_e32 v103, v4
	v_mov_b32_e32 v108, v4
	v_mov_b32_e32 v109, v4
	v_mov_b32_e32 v110, v4
	v_mov_b32_e32 v111, v4
	v_mov_b32_e32 v116, v4
	v_mov_b32_e32 v117, v4
	v_mov_b32_e32 v118, v4
	v_mov_b32_e32 v119, v4
	v_mov_b32_e32 v124, v4
	v_mov_b32_e32 v125, v4
	v_mov_b32_e32 v126, v4
	v_mov_b32_e32 v127, v4
	v_mov_b32_e32 v72, v4
	v_mov_b32_e32 v73, v4
	v_mov_b32_e32 v74, v4
	v_mov_b32_e32 v75, v4
	v_mov_b32_e32 v80, v4
	v_mov_b32_e32 v81, v4
	v_mov_b32_e32 v82, v4
	v_mov_b32_e32 v83, v4
	v_mov_b32_e32 v88, v4
	v_mov_b32_e32 v89, v4
	v_mov_b32_e32 v90, v4
	v_mov_b32_e32 v91, v4
	v_mov_b32_e32 v96, v4
	v_mov_b32_e32 v97, v4
	v_mov_b32_e32 v98, v4
	v_mov_b32_e32 v99, v4
	v_mov_b32_e32 v104, v4
	v_mov_b32_e32 v105, v4
	v_mov_b32_e32 v106, v4
	v_mov_b32_e32 v107, v4
	v_mov_b32_e32 v112, v4
	v_mov_b32_e32 v113, v4
	v_mov_b32_e32 v114, v4
	v_mov_b32_e32 v115, v4
	v_mov_b32_e32 v120, v4
	v_mov_b32_e32 v121, v4
	v_mov_b32_e32 v122, v4
	v_mov_b32_e32 v123, v4
	v_mov_b32_e32 v128, v4
	v_mov_b32_e32 v129, v4
	v_mov_b32_e32 v130, v4
	v_mov_b32_e32 v131, v4
	v_add_u32_e32 v248, 0x10000, v143
	ds_read_b128 v[146:149], v248
	ds_read_b128 v[150:153], v248 offset:1024
	ds_read_b128 v[154:157], v248 offset:2048
	ds_read_b128 v[158:161], v248 offset:3072
	ds_read_b128 v[180:183], v145
	ds_read_b128 v[184:187], v145 offset:1024
	ds_read_b128 v[188:191], v145 offset:2048
	ds_read_b128 v[192:195], v145 offset:3072
	ds_read_b128 v[196:199], v145 offset:4096
	ds_read_b128 v[200:203], v145 offset:5120
	ds_read_b128 v[208:211], v145 offset:6144
	ds_read_b128 v[212:215], v145 offset:7168
.LBB0_190:
	s_add_u32 s36, s30, 0xfff80080
	s_addc_u32 s37, s31, -1
	s_add_i32 s60, 0, 0x10000
	s_cmp_eq_u32 s59, 28
	s_cselect_b32 s41, s13, s37
	s_cselect_b32 s40, s55, s36
	s_cselect_b32 s37, s3, s58
	s_cselect_b32 s36, s56, s57
	v_lshl_add_u64 v[162:163], s[30:31], 0, v[138:139]
	s_add_i32 m0, s27, 0xc000
	global_load_lds_dwordx4 v[162:163], off
	v_lshl_add_u64 v[162:163], s[30:31], 0, v[140:141]
	s_add_i32 m0, s27, 0xe000
	s_nop 0
	global_load_lds_dwordx4 v[162:163], off
	s_waitcnt lgkmcnt(0)
	s_barrier
	s_waitcnt lgkmcnt(0)
	s_setprio 1
	s_waitcnt lgkmcnt(0)
	v_mfma_f32_16x16x32_bf16 v[128:131], v[146:149], v[180:183], v[128:131]
	v_mfma_f32_16x16x32_bf16 v[120:123], v[154:157], v[180:183], v[120:123]
	v_mfma_f32_16x16x32_bf16 v[112:115], v[146:149], v[188:191], v[112:115]
	v_mfma_f32_16x16x32_bf16 v[104:107], v[154:157], v[188:191], v[104:107]
	v_mfma_f32_16x16x32_bf16 v[96:99], v[146:149], v[196:199], v[96:99]
	v_mfma_f32_16x16x32_bf16 v[88:91], v[154:157], v[196:199], v[88:91]
	v_mfma_f32_16x16x32_bf16 v[80:83], v[146:149], v[208:211], v[80:83]
	v_mfma_f32_16x16x32_bf16 v[72:75], v[154:157], v[208:211], v[72:75]
	v_mfma_f32_16x16x32_bf16 v[128:131], v[150:153], v[184:187], v[128:131]
	v_mfma_f32_16x16x32_bf16 v[120:123], v[158:161], v[184:187], v[120:123]
	v_mfma_f32_16x16x32_bf16 v[112:115], v[150:153], v[192:195], v[112:115]
	v_mfma_f32_16x16x32_bf16 v[104:107], v[158:161], v[192:195], v[104:107]
	v_mfma_f32_16x16x32_bf16 v[96:99], v[150:153], v[200:203], v[96:99]
	v_mfma_f32_16x16x32_bf16 v[88:91], v[158:161], v[200:203], v[88:91]
	v_mfma_f32_16x16x32_bf16 v[80:83], v[150:153], v[212:215], v[80:83]
	v_mfma_f32_16x16x32_bf16 v[72:75], v[158:161], v[212:215], v[72:75]
	s_setprio 0
	s_barrier
; #define PG8_STAGE(bufoff, gbase, voff) do { _Pragma("unroll") for (int _i = 0; _i < 2; ++_i) \
;     __builtin_amdgcn_global_load_lds((const unsigned*)((const char*)(gbase) + (voff)[_i]), (LAS unsigned*)(lds + (bufoff) + ldsw + _i * 8192), 16, 0, 0); } while (0)
; #define PG8_LDA(dst, b, h) do { _Pragma("unroll") for (int m = 0; m < 4; ++m) _Pragma("unroll") for (int k = 0; k < 2; ++k) dst[m][k] = *(const LAS bf16x8*)(lds + PG8_SA(b, h) + aoff + m * 2048 + k * 1024); } while (0)
; #define PG8_LDB(dst, b, h) do { _Pragma("unroll") for (int n = 0; n < 2; ++n) _Pragma("unroll") for (int k = 0; k < 2; ++k) dst[n][k] = *(const LAS bf16x8*)(lds + PG8_SB(b, h) + boff + n * 2048 + k * 1024); } while (0)
; #define PG8_MMA(ai, bj, At, Bt) do { __builtin_amdgcn_s_setprio(1); _Pragma("unroll") for (int m = 0; m < 4; ++m) _Pragma("unroll") for (int n = 0; n < 2; ++n) _Pragma("unroll") for (int k = 0; k < 2; ++k) \
;     acc[ai][bj][m][n] = __builtin_amdgcn_mfma_f32_16x16x32_bf16(Bt[n][k], At[m][k], acc[ai][bj][m][n], 0, 0, 0); __builtin_amdgcn_s_setprio(0); } while (0)
; #define PG8_WAIT_V(n) asm volatile("s_waitcnt vmcnt(" #n ")" ::: "memory")
; #define PG8_WAIT_L(n) asm volatile("s_waitcnt lgkmcnt(" #n ")" ::: "memory")
; #define PG8_BAR __builtin_amdgcn_s_barrier()
; #define PG8_SCHED __builtin_amdgcn_sched_barrier(0)
; template <class Epi>
; DI void gemm_phase(LAS unsigned char* lds, const Gemm g, const Epi& E) {
;     ...
;       PG8_LDB(B1, 0, 1); PG8_STAGE(PG8_SB(0, 0), b2, voffB);
;       PG8_BAR; PG8_WAIT_L(0); PG8_MMA(0, 1, At, B1); PG8_BAR;
;       PG8_LDA(At, 0, 1); PG8_STAGE(PG8_SA(0, 0), a2, voffA);
;       PG8_BAR; PG8_WAIT_L(0); PG8_MMA(1, 0, At, B0); PG8_BAR; PG8_SCHED;
;       PG8_STAGE(PG8_SB(0, 1), b2 + hstepB, voffB);
;       PG8_WAIT_V(6); PG8_BAR; PG8_MMA(1, 1, At, B1); PG8_BAR;
;       PG8_LDB(B0, 1, 0); PG8_SCHED; PG8_LDA(At, 1, 0); PG8_STAGE(PG8_SA(0, 1), a2 + hstepA, voffA);
;       PG8_WAIT_L(8); PG8_BAR; PG8_WAIT_L(0); PG8_MMA(0, 0, At, B0); PG8_BAR; PG8_SCHED;
	s_add_i32 s62, 0, 0x14000
	s_add_i32 s60, s60, s47
	ds_read_b128 v[216:219], v248 offset:16384
	ds_read_b128 v[220:223], v248 offset:17408
	ds_read_b128 v[224:227], v248 offset:18432
	ds_read_b128 v[228:231], v248 offset:19456
	v_lshl_add_u64 v[162:163], s[36:37], 0, v[2:3]
	s_mov_b32 m0, s60
	v_lshl_add_u64 v[232:233], s[36:37], 0, v[132:133]
	global_load_lds_dwordx4 v[162:163], off
	s_add_i32 m0, s60, 0x2000
	s_nop 0
	global_load_lds_dwordx4 v[232:233], off
	s_waitcnt vmcnt(8)
	s_barrier
	s_waitcnt lgkmcnt(0)
	s_setprio 1
	s_waitcnt lgkmcnt(0)
	v_mfma_f32_16x16x32_bf16 v[124:127], v[216:219], v[180:183], v[124:127]
	v_mfma_f32_16x16x32_bf16 v[116:119], v[224:227], v[180:183], v[116:119]
	v_mfma_f32_16x16x32_bf16 v[108:111], v[216:219], v[188:191], v[108:111]
	ds_read_b128 v[180:183], v145 offset:16384
	v_mfma_f32_16x16x32_bf16 v[100:103], v[224:227], v[188:191], v[100:103]
	v_mfma_f32_16x16x32_bf16 v[92:95], v[216:219], v[196:199], v[92:95]
	ds_read_b128 v[188:191], v145 offset:18432
	v_mfma_f32_16x16x32_bf16 v[84:87], v[224:227], v[196:199], v[84:87]
	v_mfma_f32_16x16x32_bf16 v[76:79], v[216:219], v[208:211], v[76:79]
	ds_read_b128 v[196:199], v145 offset:20480
	v_mfma_f32_16x16x32_bf16 v[68:71], v[224:227], v[208:211], v[68:71]
	v_mfma_f32_16x16x32_bf16 v[124:127], v[220:223], v[184:187], v[124:127]
	ds_read_b128 v[208:211], v145 offset:22528
	v_mfma_f32_16x16x32_bf16 v[116:119], v[228:231], v[184:187], v[116:119]
	v_mfma_f32_16x16x32_bf16 v[108:111], v[220:223], v[192:195], v[108:111]
	ds_read_b128 v[184:187], v145 offset:17408
	v_mfma_f32_16x16x32_bf16 v[100:103], v[228:231], v[192:195], v[100:103]
	v_mfma_f32_16x16x32_bf16 v[92:95], v[220:223], v[200:203], v[92:95]
	ds_read_b128 v[192:195], v145 offset:19456
	v_mfma_f32_16x16x32_bf16 v[84:87], v[228:231], v[200:203], v[84:87]
	v_mfma_f32_16x16x32_bf16 v[76:79], v[220:223], v[212:215], v[76:79]
	ds_read_b128 v[200:203], v145 offset:21504
	v_mfma_f32_16x16x32_bf16 v[68:71], v[228:231], v[212:215], v[68:71]
	ds_read_b128 v[212:215], v145 offset:23552
	s_setprio 0
	s_mov_b32 m0, s27
	v_lshl_add_u64 v[234:235], s[40:41], 0, v[136:137]
	s_barrier
	global_load_lds_dwordx4 v[234:235], off
	v_lshl_add_u64 v[236:237], s[40:41], 0, v[134:135]
	s_mov_b32 m0, s48
	s_nop 0
	global_load_lds_dwordx4 v[236:237], off
	s_waitcnt vmcnt(8)
	s_barrier
	s_waitcnt lgkmcnt(0)
	s_setprio 1
	s_waitcnt lgkmcnt(0)
	v_mfma_f32_16x16x32_bf16 v[64:67], v[146:149], v[180:183], v[64:67]
	v_mfma_f32_16x16x32_bf16 v[56:59], v[154:157], v[180:183], v[56:59]
	v_mfma_f32_16x16x32_bf16 v[48:51], v[146:149], v[188:191], v[48:51]
	v_mfma_f32_16x16x32_bf16 v[40:43], v[154:157], v[188:191], v[40:43]
	v_mfma_f32_16x16x32_bf16 v[32:35], v[146:149], v[196:199], v[32:35]
	v_mfma_f32_16x16x32_bf16 v[24:27], v[154:157], v[196:199], v[24:27]
	v_mfma_f32_16x16x32_bf16 v[16:19], v[146:149], v[208:211], v[16:19]
	v_mfma_f32_16x16x32_bf16 v[8:11], v[154:157], v[208:211], v[8:11]
	ds_read_b128 v[146:149], v248 offset:32768
	v_mfma_f32_16x16x32_bf16 v[64:67], v[150:153], v[184:187], v[64:67]
	ds_read_b128 v[154:157], v248 offset:34816
	v_mfma_f32_16x16x32_bf16 v[56:59], v[158:161], v[184:187], v[56:59]
	v_mfma_f32_16x16x32_bf16 v[48:51], v[150:153], v[192:195], v[48:51]
	v_mfma_f32_16x16x32_bf16 v[40:43], v[158:161], v[192:195], v[40:43]
	v_mfma_f32_16x16x32_bf16 v[32:35], v[150:153], v[200:203], v[32:35]
	v_mfma_f32_16x16x32_bf16 v[24:27], v[158:161], v[200:203], v[24:27]
	v_mfma_f32_16x16x32_bf16 v[16:19], v[150:153], v[212:215], v[16:19]
	v_mfma_f32_16x16x32_bf16 v[8:11], v[158:161], v[212:215], v[8:11]
	ds_read_b128 v[150:153], v248 offset:33792
	ds_read_b128 v[158:161], v248 offset:35840
	s_setprio 0
	s_barrier
	s_add_u32 s60, s36, 0x80000
	s_addc_u32 s61, s37, 0
	s_add_i32 s62, s62, s47
	v_lshl_add_u64 v[246:247], s[60:61], 0, v[2:3]
	s_mov_b32 m0, s62
	s_nop 0
	global_load_lds_dwordx4 v[246:247], off
	v_lshl_add_u64 v[246:247], s[60:61], 0, v[132:133]
	s_add_i32 m0, s62, 0x2000
	s_nop 0
	global_load_lds_dwordx4 v[246:247], off
	s_waitcnt vmcnt(6)
	s_barrier
	s_setprio 1
	v_mfma_f32_16x16x32_bf16 v[60:63], v[216:219], v[180:183], v[60:63]
	v_mfma_f32_16x16x32_bf16 v[52:55], v[224:227], v[180:183], v[52:55]
	v_mfma_f32_16x16x32_bf16 v[44:47], v[216:219], v[188:191], v[44:47]
	ds_read_b128 v[180:183], v145 offset:32768
	v_mfma_f32_16x16x32_bf16 v[36:39], v[224:227], v[188:191], v[36:39]
	v_mfma_f32_16x16x32_bf16 v[28:31], v[216:219], v[196:199], v[28:31]
	ds_read_b128 v[188:191], v145 offset:34816
	v_mfma_f32_16x16x32_bf16 v[20:23], v[224:227], v[196:199], v[20:23]
	v_mfma_f32_16x16x32_bf16 v[12:15], v[216:219], v[208:211], v[12:15]
	ds_read_b128 v[196:199], v145 offset:36864
	v_mfma_f32_16x16x32_bf16 v[4:7], v[224:227], v[208:211], v[4:7]
	v_mfma_f32_16x16x32_bf16 v[60:63], v[220:223], v[184:187], v[60:63]
	ds_read_b128 v[208:211], v145 offset:38912
	v_mfma_f32_16x16x32_bf16 v[52:55], v[228:231], v[184:187], v[52:55]
	v_mfma_f32_16x16x32_bf16 v[44:47], v[220:223], v[192:195], v[44:47]
	ds_read_b128 v[184:187], v145 offset:33792
	v_mfma_f32_16x16x32_bf16 v[36:39], v[228:231], v[192:195], v[36:39]
	v_mfma_f32_16x16x32_bf16 v[28:31], v[220:223], v[200:203], v[28:31]
	ds_read_b128 v[192:195], v145 offset:35840
	v_mfma_f32_16x16x32_bf16 v[20:23], v[228:231], v[200:203], v[20:23]
	v_mfma_f32_16x16x32_bf16 v[12:15], v[220:223], v[212:215], v[12:15]
	ds_read_b128 v[200:203], v145 offset:37888
	v_mfma_f32_16x16x32_bf16 v[4:7], v[228:231], v[212:215], v[4:7]
	ds_read_b128 v[212:215], v145 offset:39936
	s_setprio 0
	s_add_i32 s60, 0, 0x18000
	s_barrier
; #define PG8_STAGE(bufoff, gbase, voff) do { _Pragma("unroll") for (int _i = 0; _i < 2; ++_i) \
;     __builtin_amdgcn_global_load_lds((const unsigned*)((const char*)(gbase) + (voff)[_i]), (LAS unsigned*)(lds + (bufoff) + ldsw + _i * 8192), 16, 0, 0); } while (0)
; #define PG8_LDA(dst, b, h) do { _Pragma("unroll") for (int m = 0; m < 4; ++m) _Pragma("unroll") for (int k = 0; k < 2; ++k) dst[m][k] = *(const LAS bf16x8*)(lds + PG8_SA(b, h) + aoff + m * 2048 + k * 1024); } while (0)
; #define PG8_LDB(dst, b, h) do { _Pragma("unroll") for (int n = 0; n < 2; ++n) _Pragma("unroll") for (int k = 0; k < 2; ++k) dst[n][k] = *(const LAS bf16x8*)(lds + PG8_SB(b, h) + boff + n * 2048 + k * 1024); } while (0)
; #define PG8_MMA(ai, bj, At, Bt) do { __builtin_amdgcn_s_setprio(1); _Pragma("unroll") for (int m = 0; m < 4; ++m) _Pragma("unroll") for (int n = 0; n < 2; ++n) _Pragma("unroll") for (int k = 0; k < 2; ++k) \
;     acc[ai][bj][m][n] = __builtin_amdgcn_mfma_f32_16x16x32_bf16(Bt[n][k], At[m][k], acc[ai][bj][m][n], 0, 0, 0); __builtin_amdgcn_s_setprio(0); } while (0)
; #define PG8_WAIT_V(n) asm volatile("s_waitcnt vmcnt(" #n ")" ::: "memory")
; #define PG8_WAIT_L(n) asm volatile("s_waitcnt lgkmcnt(" #n ")" ::: "memory")
; #define PG8_BAR __builtin_amdgcn_s_barrier()
; #define PG8_SCHED __builtin_amdgcn_sched_barrier(0)
; template <class Epi>
; DI void gemm_phase(LAS unsigned char* lds, const Gemm g, const Epi& E) {
;     ...
;       PG8_LDB(B0, 1, 0); PG8_SCHED; PG8_LDA(At, 1, 0); PG8_STAGE(PG8_SA(0, 1), a2 + hstepA, voffA);
;       PG8_WAIT_L(8); PG8_BAR; PG8_WAIT_L(0); PG8_MMA(0, 0, At, B0); PG8_BAR; PG8_SCHED;
;       PG8_LDB(B1, 1, 1); PG8_STAGE(PG8_SB(1, 0), b3, voffB);
;       PG8_BAR; PG8_WAIT_L(0); PG8_MMA(0, 1, At, B1); PG8_BAR;
;       PG8_LDA(At, 1, 1); PG8_STAGE(PG8_SA(1, 0), a3, voffA);
;       PG8_BAR; PG8_WAIT_L(0); PG8_MMA(1, 0, At, B0); PG8_BAR; PG8_SCHED;
;       PG8_STAGE(PG8_SB(1, 1), b3 + hstepB, voffB);
;       PG8_WAIT_V(6); PG8_BAR; PG8_MMA(1, 1, At, B1); PG8_BAR;
	s_add_u32 s40, s40, 0x80000
	s_addc_u32 s41, s41, 0
	s_mov_b32 m0, s49
	v_lshl_add_u64 v[216:217], s[40:41], 0, v[136:137]
	global_load_lds_dwordx4 v[216:217], off
	v_lshl_add_u64 v[216:217], s[40:41], 0, v[134:135]
	s_mov_b32 m0, s50
	s_nop 0
	global_load_lds_dwordx4 v[216:217], off
	s_waitcnt lgkmcnt(0)
	s_barrier
	s_waitcnt lgkmcnt(0)
	s_setprio 1
	s_waitcnt lgkmcnt(0)
	v_mfma_f32_16x16x32_bf16 v[128:131], v[146:149], v[180:183], v[128:131]
	v_mfma_f32_16x16x32_bf16 v[120:123], v[154:157], v[180:183], v[120:123]
	v_mfma_f32_16x16x32_bf16 v[112:115], v[146:149], v[188:191], v[112:115]
	v_mfma_f32_16x16x32_bf16 v[104:107], v[154:157], v[188:191], v[104:107]
	v_mfma_f32_16x16x32_bf16 v[96:99], v[146:149], v[196:199], v[96:99]
	v_mfma_f32_16x16x32_bf16 v[88:91], v[154:157], v[196:199], v[88:91]
	v_mfma_f32_16x16x32_bf16 v[80:83], v[146:149], v[208:211], v[80:83]
	v_mfma_f32_16x16x32_bf16 v[72:75], v[154:157], v[208:211], v[72:75]
	v_mfma_f32_16x16x32_bf16 v[128:131], v[150:153], v[184:187], v[128:131]
	v_mfma_f32_16x16x32_bf16 v[120:123], v[158:161], v[184:187], v[120:123]
	v_mfma_f32_16x16x32_bf16 v[112:115], v[150:153], v[192:195], v[112:115]
	v_mfma_f32_16x16x32_bf16 v[104:107], v[158:161], v[192:195], v[104:107]
	v_mfma_f32_16x16x32_bf16 v[96:99], v[150:153], v[200:203], v[96:99]
	v_mfma_f32_16x16x32_bf16 v[88:91], v[158:161], v[200:203], v[88:91]
	v_mfma_f32_16x16x32_bf16 v[80:83], v[150:153], v[212:215], v[80:83]
	v_mfma_f32_16x16x32_bf16 v[72:75], v[158:161], v[212:215], v[72:75]
	s_setprio 0
	s_barrier
	s_add_i32 s40, 0, 0x1c000
	s_add_i32 s41, s60, s47
	v_lshl_add_u64 v[162:163], v[162:163], 0, s[84:85]
	s_mov_b32 m0, s41
	ds_read_b128 v[216:219], v248 offset:49152
	ds_read_b128 v[220:223], v248 offset:50176
	ds_read_b128 v[224:227], v248 offset:51200
	ds_read_b128 v[228:231], v248 offset:52224
	global_load_lds_dwordx4 v[162:163], off
	v_lshl_add_u64 v[162:163], v[232:233], 0, s[84:85]
	s_add_i32 m0, s41, 0x2000
	s_nop 0
	global_load_lds_dwordx4 v[162:163], off
	s_waitcnt vmcnt(8)
	s_barrier
	s_waitcnt lgkmcnt(0)
	s_setprio 1
	s_waitcnt lgkmcnt(0)
	v_mfma_f32_16x16x32_bf16 v[124:127], v[216:219], v[180:183], v[124:127]
	v_mfma_f32_16x16x32_bf16 v[116:119], v[224:227], v[180:183], v[116:119]
	v_mfma_f32_16x16x32_bf16 v[108:111], v[216:219], v[188:191], v[108:111]
	ds_read_b128 v[180:183], v145 offset:49152
	v_mfma_f32_16x16x32_bf16 v[100:103], v[224:227], v[188:191], v[100:103]
	v_mfma_f32_16x16x32_bf16 v[92:95], v[216:219], v[196:199], v[92:95]
	ds_read_b128 v[188:191], v145 offset:51200
	v_mfma_f32_16x16x32_bf16 v[84:87], v[224:227], v[196:199], v[84:87]
	v_mfma_f32_16x16x32_bf16 v[76:79], v[216:219], v[208:211], v[76:79]
	ds_read_b128 v[196:199], v145 offset:53248
	v_mfma_f32_16x16x32_bf16 v[68:71], v[224:227], v[208:211], v[68:71]
	v_mfma_f32_16x16x32_bf16 v[124:127], v[220:223], v[184:187], v[124:127]
	ds_read_b128 v[208:211], v145 offset:55296
	v_mfma_f32_16x16x32_bf16 v[116:119], v[228:231], v[184:187], v[116:119]
	v_mfma_f32_16x16x32_bf16 v[108:111], v[220:223], v[192:195], v[108:111]
	ds_read_b128 v[184:187], v145 offset:50176
	v_mfma_f32_16x16x32_bf16 v[100:103], v[228:231], v[192:195], v[100:103]
	v_mfma_f32_16x16x32_bf16 v[92:95], v[220:223], v[200:203], v[92:95]
	ds_read_b128 v[192:195], v145 offset:52224
	v_mfma_f32_16x16x32_bf16 v[84:87], v[228:231], v[200:203], v[84:87]
	v_mfma_f32_16x16x32_bf16 v[76:79], v[220:223], v[212:215], v[76:79]
	ds_read_b128 v[200:203], v145 offset:54272
	v_mfma_f32_16x16x32_bf16 v[68:71], v[228:231], v[212:215], v[68:71]
	ds_read_b128 v[212:215], v145 offset:56320
	s_setprio 0
	s_mov_b32 m0, s51
	v_lshl_add_u64 v[162:163], v[234:235], 0, s[84:85]
	s_barrier
	global_load_lds_dwordx4 v[162:163], off
	v_lshl_add_u64 v[162:163], v[236:237], 0, s[84:85]
	s_mov_b32 m0, s52
	s_nop 0
	global_load_lds_dwordx4 v[162:163], off
	s_waitcnt vmcnt(8)
	s_barrier
	s_waitcnt lgkmcnt(0)
	s_setprio 1
	s_waitcnt lgkmcnt(0)
	v_mfma_f32_16x16x32_bf16 v[64:67], v[146:149], v[180:183], v[64:67]
	v_mfma_f32_16x16x32_bf16 v[56:59], v[154:157], v[180:183], v[56:59]
	v_mfma_f32_16x16x32_bf16 v[48:51], v[146:149], v[188:191], v[48:51]
	v_mfma_f32_16x16x32_bf16 v[40:43], v[154:157], v[188:191], v[40:43]
	v_mfma_f32_16x16x32_bf16 v[32:35], v[146:149], v[196:199], v[32:35]
	v_mfma_f32_16x16x32_bf16 v[24:27], v[154:157], v[196:199], v[24:27]
	v_mfma_f32_16x16x32_bf16 v[16:19], v[146:149], v[208:211], v[16:19]
	v_mfma_f32_16x16x32_bf16 v[8:11], v[154:157], v[208:211], v[8:11]
	ds_read_b128 v[146:149], v248
	v_mfma_f32_16x16x32_bf16 v[64:67], v[150:153], v[184:187], v[64:67]
	ds_read_b128 v[154:157], v248 offset:2048
	v_mfma_f32_16x16x32_bf16 v[56:59], v[158:161], v[184:187], v[56:59]
	v_mfma_f32_16x16x32_bf16 v[48:51], v[150:153], v[192:195], v[48:51]
	v_mfma_f32_16x16x32_bf16 v[40:43], v[158:161], v[192:195], v[40:43]
	v_mfma_f32_16x16x32_bf16 v[32:35], v[150:153], v[200:203], v[32:35]
	v_mfma_f32_16x16x32_bf16 v[24:27], v[158:161], v[200:203], v[24:27]
	v_mfma_f32_16x16x32_bf16 v[16:19], v[150:153], v[212:215], v[16:19]
	v_mfma_f32_16x16x32_bf16 v[8:11], v[158:161], v[212:215], v[8:11]
	ds_read_b128 v[150:153], v248 offset:1024
	ds_read_b128 v[158:161], v248 offset:3072
	s_setprio 0
	s_barrier
	s_add_u32 s36, s36, 0x80080
	s_addc_u32 s37, s37, 0
	s_add_i32 s40, s40, s47
	v_lshl_add_u64 v[246:247], s[36:37], 0, v[2:3]
	s_mov_b32 m0, s40
	s_nop 0
	global_load_lds_dwordx4 v[246:247], off
	v_lshl_add_u64 v[246:247], s[36:37], 0, v[132:133]
	s_add_i32 m0, s40, 0x2000
	s_nop 0
	global_load_lds_dwordx4 v[246:247], off
	s_waitcnt vmcnt(6)
	s_barrier
; DI unsigned cvt_pk_bf16(float lo, float hi) { const f32x2 v = {lo, hi}; const bf16x2_t r = __builtin_convertvector(v, bf16x2_t); return __builtin_bit_cast(unsigned, r); }
; #define PG8_STAGE(bufoff, gbase, voff) do { _Pragma("unroll") for (int _i = 0; _i < 2; ++_i) \
;     __builtin_amdgcn_global_load_lds((const unsigned*)((const char*)(gbase) + (voff)[_i]), (LAS unsigned*)(lds + (bufoff) + ldsw + _i * 8192), 16, 0, 0); } while (0)
; #define PG8_LDA(dst, b, h) do { _Pragma("unroll") for (int m = 0; m < 4; ++m) _Pragma("unroll") for (int k = 0; k < 2; ++k) dst[m][k] = *(const LAS bf16x8*)(lds + PG8_SA(b, h) + aoff + m * 2048 + k * 1024); } while (0)
; #define PG8_MMA(ai, bj, At, Bt) do { __builtin_amdgcn_s_setprio(1); _Pragma("unroll") for (int m = 0; m < 4; ++m) _Pragma("unroll") for (int n = 0; n < 2; ++n) _Pragma("unroll") for (int k = 0; k < 2; ++k) \
;     acc[ai][bj][m][n] = __builtin_amdgcn_mfma_f32_16x16x32_bf16(Bt[n][k], At[m][k], acc[ai][bj][m][n], 0, 0, 0); __builtin_amdgcn_s_setprio(0); } while (0)
; #define PG8_WAIT_V(n) asm volatile("s_waitcnt vmcnt(" #n ")" ::: "memory")
; template <class Epi>
; DI void gemm_phase(LAS unsigned char* lds, const Gemm g, const Epi& E) {
;     ...
;       PG8_LDA(At, 1, 1); PG8_STAGE(PG8_SA(1, 0), a3, voffA);
;       PG8_BAR; PG8_WAIT_L(0); PG8_MMA(1, 0, At, B0); PG8_BAR; PG8_SCHED;
;       PG8_STAGE(PG8_SB(1, 1), b3 + hstepB, voffB);
;       PG8_WAIT_V(6); PG8_BAR; PG8_MMA(1, 1, At, B1); PG8_BAR;
;     }
; DI float silu_f(float g) { return g * __builtin_amdgcn_rcpf(1.0f + __expf(-g)); }
;   DI void operator()(const f32x4 (&acc)[2][2][4][2], const Unit& u, int wr, int wc, int fr, int fq) const {
;     const int row0 = u.pm * BM + wr * 64 + fr, col0 = u.pn * HALF + wc * 32 + 8 * fq;
; #pragma unroll
;     for (int ai = 0; ai < 2; ++ai)
; #pragma unroll
;       for (int m = 0; m < 4; ++m) {
;         const f32x4 g0 = acc[ai][0][m][0], g1 = acc[ai][0][m][1], u0 = acc[ai][1][m][0], u1 = acc[ai][1][m][1];
;         u32x4 w;
;         w.x = cvt_pk_bf16(silu_f(g0[0]) * u0[0], silu_f(g0[1]) * u0[1]); w.y = cvt_pk_bf16(silu_f(g0[2]) * u0[2], silu_f(g0[3]) * u0[3]);
;         w.z = cvt_pk_bf16(silu_f(g1[0]) * u1[0], silu_f(g1[1]) * u1[1]); w.w = cvt_pk_bf16(silu_f(g1[2]) * u1[2], silu_f(g1[3]) * u1[3]);
;         *(u32x4*)(H + (size_t)(row0 + ai * HALF + m * 16) * DFF + col0) = w;
;       }
	s_setprio 1
	v_mfma_f32_16x16x32_bf16 v[60:63], v[216:219], v[180:183], v[60:63]
	v_mfma_f32_16x16x32_bf16 v[52:55], v[224:227], v[180:183], v[52:55]
	v_mfma_f32_16x16x32_bf16 v[44:47], v[216:219], v[188:191], v[44:47]
	ds_read_b128 v[180:183], v145
	v_mfma_f32_16x16x32_bf16 v[36:39], v[224:227], v[188:191], v[36:39]
	v_mfma_f32_16x16x32_bf16 v[28:31], v[216:219], v[196:199], v[28:31]
	ds_read_b128 v[188:191], v145 offset:2048
	v_mfma_f32_16x16x32_bf16 v[20:23], v[224:227], v[196:199], v[20:23]
	v_mfma_f32_16x16x32_bf16 v[12:15], v[216:219], v[208:211], v[12:15]
	ds_read_b128 v[196:199], v145 offset:4096
	v_mfma_f32_16x16x32_bf16 v[4:7], v[224:227], v[208:211], v[4:7]
	v_mfma_f32_16x16x32_bf16 v[60:63], v[220:223], v[184:187], v[60:63]
	ds_read_b128 v[208:211], v145 offset:6144
	v_mfma_f32_16x16x32_bf16 v[52:55], v[228:231], v[184:187], v[52:55]
	v_mfma_f32_16x16x32_bf16 v[44:47], v[220:223], v[192:195], v[44:47]
	ds_read_b128 v[184:187], v145 offset:1024
	v_mfma_f32_16x16x32_bf16 v[36:39], v[228:231], v[192:195], v[36:39]
	v_mfma_f32_16x16x32_bf16 v[28:31], v[220:223], v[200:203], v[28:31]
	ds_read_b128 v[192:195], v145 offset:3072
	v_mfma_f32_16x16x32_bf16 v[20:23], v[228:231], v[200:203], v[20:23]
	v_mfma_f32_16x16x32_bf16 v[12:15], v[220:223], v[212:215], v[12:15]
	ds_read_b128 v[200:203], v145 offset:5120
	v_mfma_f32_16x16x32_bf16 v[4:7], v[228:231], v[212:215], v[4:7]
	ds_read_b128 v[212:215], v145 offset:7168
	s_setprio 0
	s_add_i32 s59, s59, 2
	s_add_u32 s30, s30, 0x100
	s_addc_u32 s31, s31, 0
	s_add_u32 s57, s57, 0x100
	s_addc_u32 s58, s58, 0
	s_cmp_gt_u32 s59, 29
	s_barrier
	s_cbranch_scc0 .LBB0_190
	s_waitcnt lgkmcnt(0)
	v_mul_f32_e32 v147, 0xbfb8aa3b, v128
	v_exp_f32_e32 v147, v147
	v_lshl_or_b32 v148, s54, 7, v144
	v_lshl_add_u32 v146, s26, 8, v142
	v_ashrrev_i32_e32 v149, 31, v148
	v_add_f32_e32 v147, 1.0, v147
	v_rcp_f32_e32 v150, v147
	v_mul_f32_e32 v147, 0xbfb8aa3b, v129
	v_exp_f32_e32 v147, v147
	s_movk_i32 s3, 0x2c00
	s_movk_i32 s5, 0x2c00
	s_and_b64 vcc, exec, s[38:39]
	v_add_f32_e32 v147, 1.0, v147
	v_rcp_f32_e32 v151, v147
	s_mov_b32 s54, s2
	s_mov_b32 s26, s12
	s_mov_b64 s[36:37], s[22:23]
	v_pk_mul_f32 v[128:129], v[128:129], v[150:151]
	s_nop 0
	v_pk_mul_f32 v[124:125], v[128:129], v[124:125]
	s_nop 0
	v_cvt_pk_bf16_f32 v124, v124, v125
	v_mul_f32_e32 v125, 0xbfb8aa3b, v130
	v_exp_f32_e32 v125, v125
	s_nop 0
	v_add_f32_e32 v125, 1.0, v125
	v_rcp_f32_e32 v128, v125
	v_mul_f32_e32 v125, 0xbfb8aa3b, v131
	v_exp_f32_e32 v125, v125
	s_nop 0
	v_add_f32_e32 v125, 1.0, v125
	v_rcp_f32_e32 v129, v125
	s_nop 0
	v_pk_mul_f32 v[128:129], v[130:131], v[128:129]
	s_nop 0
	v_pk_mul_f32 v[126:127], v[128:129], v[126:127]
	s_nop 0
	v_cvt_pk_bf16_f32 v125, v126, v127
	v_mul_f32_e32 v126, 0xbfb8aa3b, v120
	v_mul_f32_e32 v127, 0xbfb8aa3b, v121
	v_exp_f32_e32 v126, v126
	v_exp_f32_e32 v127, v127
	v_add_f32_e32 v126, 1.0, v126
	v_add_f32_e32 v127, 1.0, v127
	v_rcp_f32_e32 v126, v126
	v_rcp_f32_e32 v127, v127
	s_nop 0
	v_pk_mul_f32 v[120:121], v[120:121], v[126:127]
	s_nop 0
	v_pk_mul_f32 v[116:117], v[120:121], v[116:117]
	s_nop 0
	v_cvt_pk_bf16_f32 v126, v116, v117
	v_mul_f32_e32 v116, 0xbfb8aa3b, v122
	v_mul_f32_e32 v117, 0xbfb8aa3b, v123
	v_exp_f32_e32 v116, v116
	v_exp_f32_e32 v117, v117
	v_add_f32_e32 v116, 1.0, v116
	v_add_f32_e32 v117, 1.0, v117
	v_rcp_f32_e32 v116, v116
	v_rcp_f32_e32 v117, v117
	s_nop 0
	v_pk_mul_f32 v[116:117], v[122:123], v[116:117]
	s_nop 0
	v_pk_mul_f32 v[116:117], v[116:117], v[118:119]
	v_lshlrev_b64 v[118:119], 1, v[148:149]
	v_cvt_pk_bf16_f32 v127, v116, v117
	v_mov_b64_e32 v[116:117], s[0:1]
	v_mad_i64_i32 v[120:121], s[30:31], v146, s3, v[116:117]
	v_lshl_add_u64 v[120:121], v[120:121], 0, v[118:119]
	global_store_dwordx4 v[120:121], v[124:127], off
	v_mul_f32_e32 v120, 0xbfb8aa3b, v112
	v_mul_f32_e32 v121, 0xbfb8aa3b, v113
	v_exp_f32_e32 v120, v120
	v_exp_f32_e32 v121, v121
	v_add_f32_e32 v120, 1.0, v120
	v_add_f32_e32 v121, 1.0, v121
	v_rcp_f32_e32 v120, v120
	v_rcp_f32_e32 v121, v121
	s_nop 0
	v_pk_mul_f32 v[112:113], v[112:113], v[120:121]
	s_nop 0
	v_pk_mul_f32 v[108:109], v[112:113], v[108:109]
	s_nop 0
	v_cvt_pk_bf16_f32 v108, v108, v109
	v_mul_f32_e32 v109, 0xbfb8aa3b, v114
	v_exp_f32_e32 v109, v109
	s_nop 0
	v_add_f32_e32 v109, 1.0, v109
	v_rcp_f32_e32 v112, v109
	v_mul_f32_e32 v109, 0xbfb8aa3b, v115
	v_exp_f32_e32 v109, v109
	s_nop 0
	v_add_f32_e32 v109, 1.0, v109
	v_rcp_f32_e32 v113, v109
	s_nop 0
	v_pk_mul_f32 v[112:113], v[114:115], v[112:113]
	s_nop 0
	v_pk_mul_f32 v[110:111], v[112:113], v[110:111]
	s_nop 0
	v_cvt_pk_bf16_f32 v109, v110, v111
	v_mul_f32_e32 v110, 0xbfb8aa3b, v104
	v_mul_f32_e32 v111, 0xbfb8aa3b, v105
	v_exp_f32_e32 v110, v110
	v_exp_f32_e32 v111, v111
	v_add_f32_e32 v110, 1.0, v110
	v_add_f32_e32 v111, 1.0, v111
	v_rcp_f32_e32 v110, v110
	v_rcp_f32_e32 v111, v111
	s_nop 0
	v_pk_mul_f32 v[104:105], v[104:105], v[110:111]
	s_nop 0
	v_pk_mul_f32 v[100:101], v[104:105], v[100:101]
	s_nop 0
	v_cvt_pk_bf16_f32 v110, v100, v101
	v_mul_f32_e32 v100, 0xbfb8aa3b, v106
	v_mul_f32_e32 v101, 0xbfb8aa3b, v107
	v_exp_f32_e32 v100, v100
	v_exp_f32_e32 v101, v101
	v_add_f32_e32 v100, 1.0, v100
	v_add_f32_e32 v101, 1.0, v101
	v_rcp_f32_e32 v100, v100
	v_rcp_f32_e32 v101, v101
	s_nop 0
	v_pk_mul_f32 v[100:101], v[106:107], v[100:101]
	s_nop 0
	v_pk_mul_f32 v[100:101], v[100:101], v[102:103]
	s_nop 0
	v_cvt_pk_bf16_f32 v111, v100, v101
	v_or_b32_e32 v100, 16, v146
	v_mad_i64_i32 v[100:101], s[30:31], v100, s3, v[116:117]
	v_lshl_add_u64 v[100:101], v[100:101], 0, v[118:119]
	global_store_dwordx4 v[100:101], v[108:111], off
	v_mul_f32_e32 v100, 0xbfb8aa3b, v96
	v_mul_f32_e32 v101, 0xbfb8aa3b, v97
; DI unsigned cvt_pk_bf16(float lo, float hi) { const f32x2 v = {lo, hi}; const bf16x2_t r = __builtin_convertvector(v, bf16x2_t); return __builtin_bit_cast(unsigned, r); }
; DI float silu_f(float g) { return g * __builtin_amdgcn_rcpf(1.0f + __expf(-g)); }
;   DI void operator()(const f32x4 (&acc)[2][2][4][2], const Unit& u, int wr, int wc, int fr, int fq) const {
;     const int row0 = u.pm * BM + wr * 64 + fr, col0 = u.pn * HALF + wc * 32 + 8 * fq;
; #pragma unroll
;     for (int ai = 0; ai < 2; ++ai)
; #pragma unroll
;       for (int m = 0; m < 4; ++m) {
;         const f32x4 g0 = acc[ai][0][m][0], g1 = acc[ai][0][m][1], u0 = acc[ai][1][m][0], u1 = acc[ai][1][m][1];
;         u32x4 w;
;         w.x = cvt_pk_bf16(silu_f(g0[0]) * u0[0], silu_f(g0[1]) * u0[1]); w.y = cvt_pk_bf16(silu_f(g0[2]) * u0[2], silu_f(g0[3]) * u0[3]);
;         w.z = cvt_pk_bf16(silu_f(g1[0]) * u1[0], silu_f(g1[1]) * u1[1]); w.w = cvt_pk_bf16(silu_f(g1[2]) * u1[2], silu_f(g1[3]) * u1[3]);
;         *(u32x4*)(H + (size_t)(row0 + ai * HALF + m * 16) * DFF + col0) = w;
;       }
	v_exp_f32_e32 v100, v100
	v_exp_f32_e32 v101, v101
	v_add_f32_e32 v100, 1.0, v100
	v_add_f32_e32 v101, 1.0, v101
	v_rcp_f32_e32 v100, v100
	v_rcp_f32_e32 v101, v101
	s_nop 0
	v_pk_mul_f32 v[96:97], v[96:97], v[100:101]
	s_nop 0
	v_pk_mul_f32 v[92:93], v[96:97], v[92:93]
	s_nop 0
	v_cvt_pk_bf16_f32 v92, v92, v93
	v_mul_f32_e32 v93, 0xbfb8aa3b, v98
	v_exp_f32_e32 v93, v93
	s_nop 0
	v_add_f32_e32 v93, 1.0, v93
	v_rcp_f32_e32 v96, v93
	v_mul_f32_e32 v93, 0xbfb8aa3b, v99
	v_exp_f32_e32 v93, v93
	s_nop 0
	v_add_f32_e32 v93, 1.0, v93
	v_rcp_f32_e32 v97, v93
	s_nop 0
	v_pk_mul_f32 v[96:97], v[98:99], v[96:97]
	s_nop 0
	v_pk_mul_f32 v[94:95], v[96:97], v[94:95]
	s_nop 0
	v_cvt_pk_bf16_f32 v93, v94, v95
	v_mul_f32_e32 v94, 0xbfb8aa3b, v88
	v_mul_f32_e32 v95, 0xbfb8aa3b, v89
	v_exp_f32_e32 v94, v94
	v_exp_f32_e32 v95, v95
	v_add_f32_e32 v94, 1.0, v94
	v_add_f32_e32 v95, 1.0, v95
	v_rcp_f32_e32 v94, v94
	v_rcp_f32_e32 v95, v95
	s_nop 0
	v_pk_mul_f32 v[88:89], v[88:89], v[94:95]
	s_nop 0
	v_pk_mul_f32 v[84:85], v[88:89], v[84:85]
	s_nop 0
	v_cvt_pk_bf16_f32 v94, v84, v85
	v_mul_f32_e32 v84, 0xbfb8aa3b, v90
	v_mul_f32_e32 v85, 0xbfb8aa3b, v91
	v_exp_f32_e32 v84, v84
	v_exp_f32_e32 v85, v85
	v_add_f32_e32 v84, 1.0, v84
	v_add_f32_e32 v85, 1.0, v85
	v_rcp_f32_e32 v84, v84
	v_rcp_f32_e32 v85, v85
	s_nop 0
	v_pk_mul_f32 v[84:85], v[90:91], v[84:85]
	s_nop 0
	v_pk_mul_f32 v[84:85], v[84:85], v[86:87]
	s_nop 0
	v_cvt_pk_bf16_f32 v95, v84, v85
	v_or_b32_e32 v84, 32, v146
	v_mad_i64_i32 v[84:85], s[30:31], v84, s3, v[116:117]
	v_lshl_add_u64 v[84:85], v[84:85], 0, v[118:119]
	global_store_dwordx4 v[84:85], v[92:95], off
	v_mul_f32_e32 v84, 0xbfb8aa3b, v80
	v_mul_f32_e32 v85, 0xbfb8aa3b, v81
	v_exp_f32_e32 v84, v84
	v_exp_f32_e32 v85, v85
	v_add_f32_e32 v84, 1.0, v84
	v_add_f32_e32 v85, 1.0, v85
	v_rcp_f32_e32 v84, v84
	v_rcp_f32_e32 v85, v85
	s_nop 0
	v_pk_mul_f32 v[80:81], v[80:81], v[84:85]
	s_nop 0
	v_pk_mul_f32 v[76:77], v[80:81], v[76:77]
	s_nop 0
	v_cvt_pk_bf16_f32 v76, v76, v77
	v_mul_f32_e32 v77, 0xbfb8aa3b, v82
	v_exp_f32_e32 v77, v77
	s_nop 0
	v_add_f32_e32 v77, 1.0, v77
	v_rcp_f32_e32 v80, v77
	v_mul_f32_e32 v77, 0xbfb8aa3b, v83
	v_exp_f32_e32 v77, v77
	s_nop 0
	v_add_f32_e32 v77, 1.0, v77
	v_rcp_f32_e32 v81, v77
	s_nop 0
	v_pk_mul_f32 v[80:81], v[82:83], v[80:81]
	s_nop 0
	v_pk_mul_f32 v[78:79], v[80:81], v[78:79]
	s_nop 0
	v_cvt_pk_bf16_f32 v77, v78, v79
	v_mul_f32_e32 v78, 0xbfb8aa3b, v72
	v_mul_f32_e32 v79, 0xbfb8aa3b, v73
	v_exp_f32_e32 v78, v78
	v_exp_f32_e32 v79, v79
	v_add_f32_e32 v78, 1.0, v78
	v_add_f32_e32 v79, 1.0, v79
	v_rcp_f32_e32 v78, v78
	v_rcp_f32_e32 v79, v79
	s_nop 0
	v_pk_mul_f32 v[72:73], v[72:73], v[78:79]
	s_nop 0
	v_pk_mul_f32 v[68:69], v[72:73], v[68:69]
	s_nop 0
	v_cvt_pk_bf16_f32 v78, v68, v69
	v_mul_f32_e32 v68, 0xbfb8aa3b, v74
	v_mul_f32_e32 v69, 0xbfb8aa3b, v75
	v_exp_f32_e32 v68, v68
	v_exp_f32_e32 v69, v69
	v_add_f32_e32 v68, 1.0, v68
	v_add_f32_e32 v69, 1.0, v69
	v_rcp_f32_e32 v68, v68
	v_rcp_f32_e32 v69, v69
	s_nop 0
	v_pk_mul_f32 v[68:69], v[74:75], v[68:69]
	s_nop 0
	v_pk_mul_f32 v[68:69], v[68:69], v[70:71]
	v_add_u32_e32 v70, 0x80, v146
	v_cvt_pk_bf16_f32 v79, v68, v69
	v_or_b32_e32 v68, 48, v146
	v_mad_i64_i32 v[68:69], s[30:31], v68, s3, v[116:117]
	v_lshl_add_u64 v[68:69], v[68:69], 0, v[118:119]
	global_store_dwordx4 v[68:69], v[76:79], off
	v_mul_f32_e32 v68, 0xbfb8aa3b, v64
	v_mul_f32_e32 v69, 0xbfb8aa3b, v65
	v_exp_f32_e32 v68, v68
	v_exp_f32_e32 v69, v69
	v_add_f32_e32 v68, 1.0, v68
	v_add_f32_e32 v69, 1.0, v69
	v_rcp_f32_e32 v68, v68
	v_rcp_f32_e32 v69, v69
	s_nop 0
	v_pk_mul_f32 v[64:65], v[64:65], v[68:69]
	s_nop 0
	v_pk_mul_f32 v[60:61], v[64:65], v[60:61]
	s_nop 0
	v_cvt_pk_bf16_f32 v60, v60, v61
	v_mul_f32_e32 v61, 0xbfb8aa3b, v66
	v_exp_f32_e32 v61, v61
	s_nop 0
	v_add_f32_e32 v61, 1.0, v61
	v_rcp_f32_e32 v64, v61
	v_mul_f32_e32 v61, 0xbfb8aa3b, v67
	v_exp_f32_e32 v61, v61
	s_nop 0
	v_add_f32_e32 v61, 1.0, v61
	v_rcp_f32_e32 v65, v61
	s_nop 0
	v_pk_mul_f32 v[64:65], v[66:67], v[64:65]
	s_nop 0
	v_pk_mul_f32 v[62:63], v[64:65], v[62:63]
	s_nop 0
	v_cvt_pk_bf16_f32 v61, v62, v63
	v_mul_f32_e32 v62, 0xbfb8aa3b, v56
	v_mul_f32_e32 v63, 0xbfb8aa3b, v57
	v_exp_f32_e32 v62, v62
	v_exp_f32_e32 v63, v63
	v_add_f32_e32 v62, 1.0, v62
	v_add_f32_e32 v63, 1.0, v63
	v_rcp_f32_e32 v62, v62
	v_rcp_f32_e32 v63, v63
	s_nop 0
	v_pk_mul_f32 v[56:57], v[56:57], v[62:63]
	s_nop 0
	v_pk_mul_f32 v[52:53], v[56:57], v[52:53]
	s_nop 0
	v_cvt_pk_bf16_f32 v62, v52, v53
	v_mul_f32_e32 v52, 0xbfb8aa3b, v58
	v_mul_f32_e32 v53, 0xbfb8aa3b, v59
	v_exp_f32_e32 v52, v52
	v_exp_f32_e32 v53, v53
	v_add_f32_e32 v52, 1.0, v52
	v_add_f32_e32 v53, 1.0, v53
	v_rcp_f32_e32 v52, v52
	v_rcp_f32_e32 v53, v53
	s_nop 0
	v_pk_mul_f32 v[52:53], v[58:59], v[52:53]
	s_nop 0
	v_pk_mul_f32 v[52:53], v[52:53], v[54:55]
	s_nop 0
	v_cvt_pk_bf16_f32 v63, v52, v53
	v_mad_i64_i32 v[52:53], s[30:31], v70, s3, v[116:117]
	v_lshl_add_u64 v[52:53], v[52:53], 0, v[118:119]
	global_store_dwordx4 v[52:53], v[60:63], off
	v_mul_f32_e32 v52, 0xbfb8aa3b, v48
	v_mul_f32_e32 v53, 0xbfb8aa3b, v49
; DI unsigned cvt_pk_bf16(float lo, float hi) { const f32x2 v = {lo, hi}; const bf16x2_t r = __builtin_convertvector(v, bf16x2_t); return __builtin_bit_cast(unsigned, r); }
; DI float silu_f(float g) { return g * __builtin_amdgcn_rcpf(1.0f + __expf(-g)); }
;   DI void operator()(const f32x4 (&acc)[2][2][4][2], const Unit& u, int wr, int wc, int fr, int fq) const {
;     const int row0 = u.pm * BM + wr * 64 + fr, col0 = u.pn * HALF + wc * 32 + 8 * fq;
; #pragma unroll
;     for (int ai = 0; ai < 2; ++ai)
; #pragma unroll
;       for (int m = 0; m < 4; ++m) {
;         const f32x4 g0 = acc[ai][0][m][0], g1 = acc[ai][0][m][1], u0 = acc[ai][1][m][0], u1 = acc[ai][1][m][1];
;         u32x4 w;
;         w.x = cvt_pk_bf16(silu_f(g0[0]) * u0[0], silu_f(g0[1]) * u0[1]); w.y = cvt_pk_bf16(silu_f(g0[2]) * u0[2], silu_f(g0[3]) * u0[3]);
;         w.z = cvt_pk_bf16(silu_f(g1[0]) * u1[0], silu_f(g1[1]) * u1[1]); w.w = cvt_pk_bf16(silu_f(g1[2]) * u1[2], silu_f(g1[3]) * u1[3]);
;         *(u32x4*)(H + (size_t)(row0 + ai * HALF + m * 16) * DFF + col0) = w;
;       }
	v_exp_f32_e32 v52, v52
	v_exp_f32_e32 v53, v53
	v_add_f32_e32 v52, 1.0, v52
	v_add_f32_e32 v53, 1.0, v53
	v_rcp_f32_e32 v52, v52
	v_rcp_f32_e32 v53, v53
	s_nop 0
	v_pk_mul_f32 v[48:49], v[48:49], v[52:53]
	s_nop 0
	v_pk_mul_f32 v[44:45], v[48:49], v[44:45]
	s_nop 0
	v_cvt_pk_bf16_f32 v44, v44, v45
	v_mul_f32_e32 v45, 0xbfb8aa3b, v50
	v_exp_f32_e32 v45, v45
	s_nop 0
	v_add_f32_e32 v45, 1.0, v45
	v_rcp_f32_e32 v48, v45
	v_mul_f32_e32 v45, 0xbfb8aa3b, v51
	v_exp_f32_e32 v45, v45
	s_nop 0
	v_add_f32_e32 v45, 1.0, v45
	v_rcp_f32_e32 v49, v45
	s_nop 0
	v_pk_mul_f32 v[48:49], v[50:51], v[48:49]
	s_nop 0
	v_pk_mul_f32 v[46:47], v[48:49], v[46:47]
	s_nop 0
	v_cvt_pk_bf16_f32 v45, v46, v47
	v_mul_f32_e32 v46, 0xbfb8aa3b, v40
	v_mul_f32_e32 v47, 0xbfb8aa3b, v41
	v_exp_f32_e32 v46, v46
	v_exp_f32_e32 v47, v47
	v_add_f32_e32 v46, 1.0, v46
	v_add_f32_e32 v47, 1.0, v47
	v_rcp_f32_e32 v46, v46
	v_rcp_f32_e32 v47, v47
	s_nop 0
	v_pk_mul_f32 v[40:41], v[40:41], v[46:47]
	s_nop 0
	v_pk_mul_f32 v[36:37], v[40:41], v[36:37]
	s_nop 0
	v_cvt_pk_bf16_f32 v46, v36, v37
	v_mul_f32_e32 v36, 0xbfb8aa3b, v42
	v_mul_f32_e32 v37, 0xbfb8aa3b, v43
	v_exp_f32_e32 v36, v36
	v_exp_f32_e32 v37, v37
	v_add_f32_e32 v36, 1.0, v36
	v_add_f32_e32 v37, 1.0, v37
	v_rcp_f32_e32 v36, v36
	v_rcp_f32_e32 v37, v37
	s_nop 0
	v_pk_mul_f32 v[36:37], v[42:43], v[36:37]
	s_nop 0
	v_pk_mul_f32 v[36:37], v[36:37], v[38:39]
	s_nop 0
	v_cvt_pk_bf16_f32 v47, v36, v37
	v_add_u32_e32 v36, 0x90, v146
	v_mad_i64_i32 v[36:37], s[30:31], v36, s3, v[116:117]
	v_lshl_add_u64 v[36:37], v[36:37], 0, v[118:119]
	global_store_dwordx4 v[36:37], v[44:47], off
	v_mul_f32_e32 v36, 0xbfb8aa3b, v32
	v_mul_f32_e32 v37, 0xbfb8aa3b, v33
	v_exp_f32_e32 v36, v36
	v_exp_f32_e32 v37, v37
	v_add_f32_e32 v36, 1.0, v36
	v_add_f32_e32 v37, 1.0, v37
	v_rcp_f32_e32 v36, v36
	v_rcp_f32_e32 v37, v37
	s_nop 0
	v_pk_mul_f32 v[32:33], v[32:33], v[36:37]
	s_nop 0
	v_pk_mul_f32 v[28:29], v[32:33], v[28:29]
	s_nop 0
	v_cvt_pk_bf16_f32 v28, v28, v29
	v_mul_f32_e32 v29, 0xbfb8aa3b, v34
	v_exp_f32_e32 v29, v29
	s_nop 0
	v_add_f32_e32 v29, 1.0, v29
	v_rcp_f32_e32 v32, v29
	v_mul_f32_e32 v29, 0xbfb8aa3b, v35
	v_exp_f32_e32 v29, v29
	s_nop 0
	v_add_f32_e32 v29, 1.0, v29
	v_rcp_f32_e32 v33, v29
	s_nop 0
	v_pk_mul_f32 v[32:33], v[34:35], v[32:33]
	s_nop 0
	v_pk_mul_f32 v[30:31], v[32:33], v[30:31]
	s_nop 0
	v_cvt_pk_bf16_f32 v29, v30, v31
	v_mul_f32_e32 v30, 0xbfb8aa3b, v24
	v_mul_f32_e32 v31, 0xbfb8aa3b, v25
	v_exp_f32_e32 v30, v30
	v_exp_f32_e32 v31, v31
	v_add_f32_e32 v30, 1.0, v30
	v_add_f32_e32 v31, 1.0, v31
	v_rcp_f32_e32 v30, v30
	v_rcp_f32_e32 v31, v31
	s_nop 0
	v_pk_mul_f32 v[24:25], v[24:25], v[30:31]
	s_nop 0
	v_pk_mul_f32 v[20:21], v[24:25], v[20:21]
	s_nop 0
	v_cvt_pk_bf16_f32 v30, v20, v21
	v_mul_f32_e32 v20, 0xbfb8aa3b, v26
	v_mul_f32_e32 v21, 0xbfb8aa3b, v27
	v_exp_f32_e32 v20, v20
	v_exp_f32_e32 v21, v21
	v_add_f32_e32 v20, 1.0, v20
	v_add_f32_e32 v21, 1.0, v21
	v_rcp_f32_e32 v20, v20
	v_rcp_f32_e32 v21, v21
	s_nop 0
	v_pk_mul_f32 v[20:21], v[26:27], v[20:21]
	s_nop 0
	v_pk_mul_f32 v[20:21], v[20:21], v[22:23]
	s_nop 0
	v_cvt_pk_bf16_f32 v31, v20, v21
	v_add_u32_e32 v20, 0xa0, v146
	v_mad_i64_i32 v[20:21], s[30:31], v20, s3, v[116:117]
	v_lshl_add_u64 v[20:21], v[20:21], 0, v[118:119]
	global_store_dwordx4 v[20:21], v[28:31], off
	v_mul_f32_e32 v20, 0xbfb8aa3b, v16
	v_mul_f32_e32 v21, 0xbfb8aa3b, v17
	v_exp_f32_e32 v20, v20
	v_exp_f32_e32 v21, v21
	v_add_f32_e32 v20, 1.0, v20
	v_add_f32_e32 v21, 1.0, v21
	v_rcp_f32_e32 v20, v20
	v_rcp_f32_e32 v21, v21
	s_nop 0
	v_pk_mul_f32 v[16:17], v[16:17], v[20:21]
	s_nop 0
	v_pk_mul_f32 v[12:13], v[16:17], v[12:13]
	s_nop 0
	v_cvt_pk_bf16_f32 v12, v12, v13
	v_mul_f32_e32 v13, 0xbfb8aa3b, v18
	v_exp_f32_e32 v13, v13
	s_nop 0
	v_add_f32_e32 v13, 1.0, v13
	v_rcp_f32_e32 v16, v13
	v_mul_f32_e32 v13, 0xbfb8aa3b, v19
	v_exp_f32_e32 v13, v13
	s_nop 0
	v_add_f32_e32 v13, 1.0, v13
	v_rcp_f32_e32 v17, v13
	s_nop 0
	v_pk_mul_f32 v[16:17], v[18:19], v[16:17]
	s_nop 0
	v_pk_mul_f32 v[14:15], v[16:17], v[14:15]
	s_nop 0
	v_cvt_pk_bf16_f32 v13, v14, v15
	v_mul_f32_e32 v14, 0xbfb8aa3b, v8
	v_mul_f32_e32 v15, 0xbfb8aa3b, v9
	v_exp_f32_e32 v14, v14
	v_exp_f32_e32 v15, v15
	v_add_f32_e32 v14, 1.0, v14
	v_add_f32_e32 v15, 1.0, v15
	v_rcp_f32_e32 v14, v14
	v_rcp_f32_e32 v15, v15
	s_nop 0
	v_pk_mul_f32 v[8:9], v[8:9], v[14:15]
	s_nop 0
	v_pk_mul_f32 v[4:5], v[8:9], v[4:5]
	s_nop 0
	v_cvt_pk_bf16_f32 v14, v4, v5
	v_mul_f32_e32 v4, 0xbfb8aa3b, v10
	v_mul_f32_e32 v5, 0xbfb8aa3b, v11
	v_exp_f32_e32 v4, v4
	v_exp_f32_e32 v5, v5
	v_add_f32_e32 v4, 1.0, v4
	v_add_f32_e32 v5, 1.0, v5
	v_rcp_f32_e32 v4, v4
	v_rcp_f32_e32 v5, v5
	s_nop 0
	v_pk_mul_f32 v[4:5], v[10:11], v[4:5]
	s_nop 0
	v_pk_mul_f32 v[4:5], v[4:5], v[6:7]
	s_nop 0
	v_cvt_pk_bf16_f32 v15, v4, v5
	v_add_u32_e32 v4, 0xb0, v146
	v_mad_i64_i32 v[4:5], s[30:31], v4, s3, v[116:117]
	v_lshl_add_u64 v[4:5], v[4:5], 0, v[118:119]
	s_mov_b64 s[30:31], s[18:19]
	global_store_dwordx4 v[4:5], v[12:15], off
	s_cbranch_vccz .LBB0_187
	s_waitcnt vmcnt(0)
	s_cmpk_gt_u32 s25, 0xff
	s_cbranch_scc1 .LBB0_194
	s_barrier

; #define PG8_STAGE(bufoff, gbase, voff) do { _Pragma("unroll") for (int _i = 0; _i < 2; ++_i) \
;     __builtin_amdgcn_global_load_lds((const unsigned*)((const char*)(gbase) + (voff)[_i]), (LAS unsigned*)(lds + (bufoff) + ldsw + _i * 8192), 16, 0, 0); } while (0)
; #define PG8_LDA(dst, b, h) do { _Pragma("unroll") for (int m = 0; m < 4; ++m) _Pragma("unroll") for (int k = 0; k < 2; ++k) dst[m][k] = *(const LAS bf16x8*)(lds + PG8_SA(b, h) + aoff + m * 2048 + k * 1024); } while (0)
; #define PG8_LDB(dst, b, h) do { _Pragma("unroll") for (int n = 0; n < 2; ++n) _Pragma("unroll") for (int k = 0; k < 2; ++k) dst[n][k] = *(const LAS bf16x8*)(lds + PG8_SB(b, h) + boff + n * 2048 + k * 1024); } while (0)
; #define PG8_MMA(ai, bj, At, Bt) do { __builtin_amdgcn_s_setprio(1); _Pragma("unroll") for (int m = 0; m < 4; ++m) _Pragma("unroll") for (int n = 0; n < 2; ++n) _Pragma("unroll") for (int k = 0; k < 2; ++k) \
;     acc[ai][bj][m][n] = __builtin_amdgcn_mfma_f32_16x16x32_bf16(Bt[n][k], At[m][k], acc[ai][bj][m][n], 0, 0, 0); __builtin_amdgcn_s_setprio(0); } while (0)
; #define PG8_WAIT_L(n) asm volatile("s_waitcnt lgkmcnt(" #n ")" ::: "memory")
; #define PG8_BAR __builtin_amdgcn_s_barrier()
; #define PG8_SCHED __builtin_amdgcn_sched_barrier(0)
; template <class Epi>
; DI void gemm_phase(LAS unsigned char* lds, const Gemm g, const Epi& E) {
;     ...
;     for (int t = 0; t < nt; t += 2) {
;       const bool last = (t == nt - 2);
;       const char* a1 = cA + (size_t)(t + 1) * kstep;
;       const char* a2 = last ? nA : cA + (size_t)(t + 2) * kstep; const char* b2 = last ? nB : cB + (size_t)(t + 2) * kstep;
;       const char* a3 = a2 + kstep; const char* b3 = b2 + kstep;
;       PG8_LDB(B0, 0, 0); PG8_SCHED; PG8_LDA(At, 0, 0); PG8_STAGE(PG8_SA(1, 1), a1 + hstepA, voffA);
;       PG8_WAIT_L(8); PG8_BAR; PG8_WAIT_L(0); PG8_MMA(0, 0, At, B0); PG8_BAR; PG8_SCHED;
;     ...
; #pragma unroll
;     for (int a = 0; a < 2; ++a)
; #pragma unroll
;       for (int b = 0; b < 2; ++b)
; #pragma unroll
;         for (int m = 0; m < 4; ++m)
; #pragma unroll
;           for (int n = 0; n < 2; ++n) acc[a][b][m][n] = (f32x4){0.f, 0.f, 0.f, 0.f};
;     cur = nxt; cA = nA; cB = nB; ++ui;
.LBB0_224:
	s_ashr_i32 s27, s26, 31
	v_cmp_lt_i64_e32 vcc, s[30:31], v[174:175]
	s_lshl_b64 s[30:31], s[26:27], 20
	s_add_u32 s30, s49, s30
	s_addc_u32 s31, s50, s31
	s_and_b64 s[36:37], vcc, exec
	s_cselect_b32 s27, s31, s43
	s_cselect_b32 s41, s30, s42
	s_ashr_i32 s23, s22, 31
	s_lshl_b64 s[36:37], s[22:23], 20
	s_add_u32 s36, s51, s36
	s_addc_u32 s37, s52, s37
	s_and_b64 s[46:47], vcc, exec
	s_cselect_b32 s23, s37, s45
	s_cselect_b32 s63, s36, s44
	s_add_u32 s42, s42, 0x80080
	s_addc_u32 s43, s43, 0
	s_add_u32 s64, s44, 0x100
	v_mov_b32_e32 v4, 0
	s_addc_u32 s65, s45, 0
	s_mov_b32 s66, -2
	v_mov_b32_e32 v5, v4
	v_mov_b32_e32 v6, v4
	v_mov_b32_e32 v7, v4
	v_mov_b32_e32 v8, v4
	v_mov_b32_e32 v9, v4
	v_mov_b32_e32 v10, v4
	v_mov_b32_e32 v11, v4
	v_mov_b32_e32 v12, v4
	v_mov_b32_e32 v13, v4
	v_mov_b32_e32 v14, v4
	v_mov_b32_e32 v15, v4
	v_mov_b32_e32 v16, v4
	v_mov_b32_e32 v17, v4
	v_mov_b32_e32 v18, v4
	v_mov_b32_e32 v19, v4
	v_mov_b32_e32 v28, v4
	v_mov_b32_e32 v29, v4
	v_mov_b32_e32 v30, v4
	v_mov_b32_e32 v31, v4
	v_mov_b32_e32 v32, v4
	v_mov_b32_e32 v33, v4
	v_mov_b32_e32 v34, v4
	v_mov_b32_e32 v35, v4
	v_mov_b32_e32 v44, v4
	v_mov_b32_e32 v45, v4
	v_mov_b32_e32 v46, v4
	v_mov_b32_e32 v47, v4
	v_mov_b32_e32 v48, v4
	v_mov_b32_e32 v49, v4
	v_mov_b32_e32 v50, v4
	v_mov_b32_e32 v51, v4
	v_mov_b32_e32 v20, v4
	v_mov_b32_e32 v21, v4
	v_mov_b32_e32 v22, v4
	v_mov_b32_e32 v23, v4
	v_mov_b32_e32 v24, v4
	v_mov_b32_e32 v25, v4
	v_mov_b32_e32 v26, v4
	v_mov_b32_e32 v27, v4
	v_mov_b32_e32 v36, v4
	v_mov_b32_e32 v37, v4
	v_mov_b32_e32 v38, v4
	v_mov_b32_e32 v39, v4
	v_mov_b32_e32 v40, v4
	v_mov_b32_e32 v41, v4
	v_mov_b32_e32 v42, v4
	v_mov_b32_e32 v43, v4
	v_mov_b32_e32 v52, v4
	v_mov_b32_e32 v53, v4
	v_mov_b32_e32 v54, v4
	v_mov_b32_e32 v55, v4
	v_mov_b32_e32 v56, v4
	v_mov_b32_e32 v57, v4
	v_mov_b32_e32 v58, v4
	v_mov_b32_e32 v59, v4
	v_mov_b32_e32 v60, v4
	v_mov_b32_e32 v61, v4
	v_mov_b32_e32 v62, v4
	v_mov_b32_e32 v63, v4
	v_mov_b32_e32 v64, v4
	v_mov_b32_e32 v65, v4
	v_mov_b32_e32 v66, v4
	v_mov_b32_e32 v67, v4
	v_mov_b32_e32 v68, v4
	v_mov_b32_e32 v69, v4
	v_mov_b32_e32 v70, v4
	v_mov_b32_e32 v71, v4
	v_mov_b32_e32 v72, v4
	v_mov_b32_e32 v73, v4
	v_mov_b32_e32 v74, v4
	v_mov_b32_e32 v75, v4
	v_mov_b32_e32 v76, v4
	v_mov_b32_e32 v77, v4
	v_mov_b32_e32 v78, v4
	v_mov_b32_e32 v79, v4
	v_mov_b32_e32 v80, v4
	v_mov_b32_e32 v81, v4
	v_mov_b32_e32 v82, v4
	v_mov_b32_e32 v83, v4
	v_mov_b32_e32 v92, v4
	v_mov_b32_e32 v93, v4
	v_mov_b32_e32 v94, v4
	v_mov_b32_e32 v95, v4
	v_mov_b32_e32 v96, v4
	v_mov_b32_e32 v97, v4
	v_mov_b32_e32 v98, v4
	v_mov_b32_e32 v99, v4
	v_mov_b32_e32 v108, v4
	v_mov_b32_e32 v109, v4
	v_mov_b32_e32 v110, v4
	v_mov_b32_e32 v111, v4
	v_mov_b32_e32 v112, v4
	v_mov_b32_e32 v113, v4
	v_mov_b32_e32 v114, v4
	v_mov_b32_e32 v115, v4
	v_mov_b32_e32 v84, v4
	v_mov_b32_e32 v85, v4
	v_mov_b32_e32 v86, v4
	v_mov_b32_e32 v87, v4
	v_mov_b32_e32 v88, v4
	v_mov_b32_e32 v89, v4
	v_mov_b32_e32 v90, v4
	v_mov_b32_e32 v91, v4
	v_mov_b32_e32 v100, v4
	v_mov_b32_e32 v101, v4
	v_mov_b32_e32 v102, v4
	v_mov_b32_e32 v103, v4
	v_mov_b32_e32 v104, v4
	v_mov_b32_e32 v105, v4
	v_mov_b32_e32 v106, v4
	v_mov_b32_e32 v107, v4
	v_mov_b32_e32 v116, v4
	v_mov_b32_e32 v117, v4
	v_mov_b32_e32 v118, v4
	v_mov_b32_e32 v119, v4
	v_mov_b32_e32 v120, v4
	v_mov_b32_e32 v121, v4
	v_mov_b32_e32 v122, v4
	v_mov_b32_e32 v123, v4
	v_mov_b32_e32 v124, v4
	v_mov_b32_e32 v125, v4
	v_mov_b32_e32 v126, v4
	v_mov_b32_e32 v127, v4
	v_mov_b32_e32 v128, v4
	v_mov_b32_e32 v129, v4
	v_mov_b32_e32 v130, v4
	v_mov_b32_e32 v131, v4
	v_add_u32_e32 v248, 0x10000, v151
	ds_read_b128 v[156:159], v248
	ds_read_b128 v[160:163], v248 offset:1024
	ds_read_b128 v[180:183], v248 offset:2048
	ds_read_b128 v[184:187], v248 offset:3072
	ds_read_b128 v[188:191], v154
	ds_read_b128 v[192:195], v154 offset:1024
	ds_read_b128 v[196:199], v154 offset:2048
	ds_read_b128 v[200:203], v154 offset:3072
	ds_read_b128 v[208:211], v154 offset:4096
	ds_read_b128 v[212:215], v154 offset:5120
	ds_read_b128 v[216:219], v154 offset:6144
	ds_read_b128 v[220:223], v154 offset:7168
.LBB0_225:
	s_add_u32 s44, s42, 0xfff80080
	s_addc_u32 s45, s43, -1
	s_add_i32 s67, 0, 0x10000
	s_cmp_eq_u32 s66, 28
	s_cselect_b32 s47, s27, s45
	s_cselect_b32 s46, s41, s44
	s_cselect_b32 s45, s23, s65
	s_cselect_b32 s44, s63, s64
	v_lshl_add_u64 v[148:149], s[42:43], 0, v[144:145]
	s_add_i32 m0, s55, 0xc000
	global_load_lds_dwordx4 v[148:149], off
	v_lshl_add_u64 v[148:149], s[42:43], 0, v[146:147]
	s_add_i32 m0, s55, 0xe000
	s_nop 0
	global_load_lds_dwordx4 v[148:149], off
	s_waitcnt lgkmcnt(0)
	s_barrier
	s_waitcnt lgkmcnt(0)
	s_setprio 1
	s_waitcnt lgkmcnt(0)
	v_mfma_f32_16x16x32_bf16 v[128:131], v[156:159], v[188:191], v[128:131]
	v_mfma_f32_16x16x32_bf16 v[124:127], v[180:183], v[188:191], v[124:127]
	v_mfma_f32_16x16x32_bf16 v[120:123], v[156:159], v[196:199], v[120:123]
	v_mfma_f32_16x16x32_bf16 v[116:119], v[180:183], v[196:199], v[116:119]
	v_mfma_f32_16x16x32_bf16 v[104:107], v[156:159], v[208:211], v[104:107]
	v_mfma_f32_16x16x32_bf16 v[100:103], v[180:183], v[208:211], v[100:103]
	v_mfma_f32_16x16x32_bf16 v[88:91], v[156:159], v[216:219], v[88:91]
	v_mfma_f32_16x16x32_bf16 v[84:87], v[180:183], v[216:219], v[84:87]
	v_mfma_f32_16x16x32_bf16 v[128:131], v[160:163], v[192:195], v[128:131]
	v_mfma_f32_16x16x32_bf16 v[124:127], v[184:187], v[192:195], v[124:127]
	v_mfma_f32_16x16x32_bf16 v[120:123], v[160:163], v[200:203], v[120:123]
	v_mfma_f32_16x16x32_bf16 v[116:119], v[184:187], v[200:203], v[116:119]
	v_mfma_f32_16x16x32_bf16 v[104:107], v[160:163], v[212:215], v[104:107]
	v_mfma_f32_16x16x32_bf16 v[100:103], v[184:187], v[212:215], v[100:103]
	v_mfma_f32_16x16x32_bf16 v[88:91], v[160:163], v[220:223], v[88:91]
	v_mfma_f32_16x16x32_bf16 v[84:87], v[184:187], v[220:223], v[84:87]
	s_setprio 0
	s_barrier
; #define PG8_STAGE(bufoff, gbase, voff) do { _Pragma("unroll") for (int _i = 0; _i < 2; ++_i) \
;     __builtin_amdgcn_global_load_lds((const unsigned*)((const char*)(gbase) + (voff)[_i]), (LAS unsigned*)(lds + (bufoff) + ldsw + _i * 8192), 16, 0, 0); } while (0)
; #define PG8_LDA(dst, b, h) do { _Pragma("unroll") for (int m = 0; m < 4; ++m) _Pragma("unroll") for (int k = 0; k < 2; ++k) dst[m][k] = *(const LAS bf16x8*)(lds + PG8_SA(b, h) + aoff + m * 2048 + k * 1024); } while (0)
; #define PG8_LDB(dst, b, h) do { _Pragma("unroll") for (int n = 0; n < 2; ++n) _Pragma("unroll") for (int k = 0; k < 2; ++k) dst[n][k] = *(const LAS bf16x8*)(lds + PG8_SB(b, h) + boff + n * 2048 + k * 1024); } while (0)
; #define PG8_MMA(ai, bj, At, Bt) do { __builtin_amdgcn_s_setprio(1); _Pragma("unroll") for (int m = 0; m < 4; ++m) _Pragma("unroll") for (int n = 0; n < 2; ++n) _Pragma("unroll") for (int k = 0; k < 2; ++k) \
;     acc[ai][bj][m][n] = __builtin_amdgcn_mfma_f32_16x16x32_bf16(Bt[n][k], At[m][k], acc[ai][bj][m][n], 0, 0, 0); __builtin_amdgcn_s_setprio(0); } while (0)
; #define PG8_WAIT_V(n) asm volatile("s_waitcnt vmcnt(" #n ")" ::: "memory")
; #define PG8_WAIT_L(n) asm volatile("s_waitcnt lgkmcnt(" #n ")" ::: "memory")
; #define PG8_BAR __builtin_amdgcn_s_barrier()
; #define PG8_SCHED __builtin_amdgcn_sched_barrier(0)
; template <class Epi>
; DI void gemm_phase(LAS unsigned char* lds, const Gemm g, const Epi& E) {
;     ...
;       PG8_LDB(B1, 0, 1); PG8_STAGE(PG8_SB(0, 0), b2, voffB);
;       PG8_BAR; PG8_WAIT_L(0); PG8_MMA(0, 1, At, B1); PG8_BAR;
;       PG8_LDA(At, 0, 1); PG8_STAGE(PG8_SA(0, 0), a2, voffA);
;       PG8_BAR; PG8_WAIT_L(0); PG8_MMA(1, 0, At, B0); PG8_BAR; PG8_SCHED;
;       PG8_STAGE(PG8_SB(0, 1), b2 + hstepB, voffB);
;       PG8_WAIT_V(6); PG8_BAR; PG8_MMA(1, 1, At, B1); PG8_BAR;
;       PG8_LDB(B0, 1, 0); PG8_SCHED; PG8_LDA(At, 1, 0); PG8_STAGE(PG8_SA(0, 1), a2 + hstepA, voffA);
;       PG8_WAIT_L(8); PG8_BAR; PG8_WAIT_L(0); PG8_MMA(0, 0, At, B0); PG8_BAR; PG8_SCHED;
;       PG8_LDB(B1, 1, 1); PG8_STAGE(PG8_SB(1, 0), b3, voffB);
;       PG8_BAR; PG8_WAIT_L(0); PG8_MMA(0, 1, At, B1); PG8_BAR;
	s_add_i32 s70, 0, 0x14000
	s_add_i32 s67, s67, s54
	v_lshl_add_u64 v[148:149], s[44:45], 0, v[136:137]
	s_mov_b32 m0, s67
	ds_read_b128 v[224:227], v248 offset:16384
	ds_read_b128 v[228:231], v248 offset:17408
	ds_read_b128 v[232:235], v248 offset:18432
	ds_read_b128 v[236:239], v248 offset:19456
	global_load_lds_dwordx4 v[148:149], off
	v_lshl_add_u64 v[240:241], s[44:45], 0, v[132:133]
	s_add_i32 m0, s67, 0x2000
	s_nop 0
	global_load_lds_dwordx4 v[240:241], off
	s_waitcnt vmcnt(8)
	s_barrier
	s_waitcnt lgkmcnt(0)
	s_setprio 1
	s_waitcnt lgkmcnt(0)
	v_mfma_f32_16x16x32_bf16 v[112:115], v[224:227], v[188:191], v[112:115]
	v_mfma_f32_16x16x32_bf16 v[108:111], v[232:235], v[188:191], v[108:111]
	v_mfma_f32_16x16x32_bf16 v[96:99], v[224:227], v[196:199], v[96:99]
	ds_read_b128 v[188:191], v154 offset:16384
	v_mfma_f32_16x16x32_bf16 v[92:95], v[232:235], v[196:199], v[92:95]
	v_mfma_f32_16x16x32_bf16 v[80:83], v[224:227], v[208:211], v[80:83]
	ds_read_b128 v[196:199], v154 offset:18432
	v_mfma_f32_16x16x32_bf16 v[76:79], v[232:235], v[208:211], v[76:79]
	v_mfma_f32_16x16x32_bf16 v[72:75], v[224:227], v[216:219], v[72:75]
	ds_read_b128 v[208:211], v154 offset:20480
	v_mfma_f32_16x16x32_bf16 v[68:71], v[232:235], v[216:219], v[68:71]
	v_mfma_f32_16x16x32_bf16 v[112:115], v[228:231], v[192:195], v[112:115]
	ds_read_b128 v[216:219], v154 offset:22528
	v_mfma_f32_16x16x32_bf16 v[108:111], v[236:239], v[192:195], v[108:111]
	v_mfma_f32_16x16x32_bf16 v[96:99], v[228:231], v[200:203], v[96:99]
	ds_read_b128 v[192:195], v154 offset:17408
	v_mfma_f32_16x16x32_bf16 v[92:95], v[236:239], v[200:203], v[92:95]
	v_mfma_f32_16x16x32_bf16 v[80:83], v[228:231], v[212:215], v[80:83]
	ds_read_b128 v[200:203], v154 offset:19456
	v_mfma_f32_16x16x32_bf16 v[76:79], v[236:239], v[212:215], v[76:79]
	v_mfma_f32_16x16x32_bf16 v[72:75], v[228:231], v[220:223], v[72:75]
	ds_read_b128 v[212:215], v154 offset:21504
	v_mfma_f32_16x16x32_bf16 v[68:71], v[236:239], v[220:223], v[68:71]
	ds_read_b128 v[220:223], v154 offset:23552
	s_setprio 0
	s_mov_b32 m0, s55
	v_lshl_add_u64 v[242:243], s[46:47], 0, v[138:139]
	s_barrier
	global_load_lds_dwordx4 v[242:243], off
	v_lshl_add_u64 v[244:245], s[46:47], 0, v[134:135]
	s_mov_b32 m0, s56
	s_nop 0
	global_load_lds_dwordx4 v[244:245], off
	s_waitcnt vmcnt(8)
	s_barrier
	s_waitcnt lgkmcnt(0)
	s_setprio 1
	s_waitcnt lgkmcnt(0)
	v_mfma_f32_16x16x32_bf16 v[64:67], v[156:159], v[188:191], v[64:67]
	v_mfma_f32_16x16x32_bf16 v[60:63], v[180:183], v[188:191], v[60:63]
	v_mfma_f32_16x16x32_bf16 v[56:59], v[156:159], v[196:199], v[56:59]
	v_mfma_f32_16x16x32_bf16 v[52:55], v[180:183], v[196:199], v[52:55]
	v_mfma_f32_16x16x32_bf16 v[40:43], v[156:159], v[208:211], v[40:43]
	v_mfma_f32_16x16x32_bf16 v[36:39], v[180:183], v[208:211], v[36:39]
	v_mfma_f32_16x16x32_bf16 v[24:27], v[156:159], v[216:219], v[24:27]
	v_mfma_f32_16x16x32_bf16 v[20:23], v[180:183], v[216:219], v[20:23]
	ds_read_b128 v[156:159], v248 offset:32768
	v_mfma_f32_16x16x32_bf16 v[64:67], v[160:163], v[192:195], v[64:67]
	ds_read_b128 v[180:183], v248 offset:34816
	v_mfma_f32_16x16x32_bf16 v[60:63], v[184:187], v[192:195], v[60:63]
	v_mfma_f32_16x16x32_bf16 v[56:59], v[160:163], v[200:203], v[56:59]
	v_mfma_f32_16x16x32_bf16 v[52:55], v[184:187], v[200:203], v[52:55]
	v_mfma_f32_16x16x32_bf16 v[40:43], v[160:163], v[212:215], v[40:43]
	v_mfma_f32_16x16x32_bf16 v[36:39], v[184:187], v[212:215], v[36:39]
	v_mfma_f32_16x16x32_bf16 v[24:27], v[160:163], v[220:223], v[24:27]
	v_mfma_f32_16x16x32_bf16 v[20:23], v[184:187], v[220:223], v[20:23]
	ds_read_b128 v[160:163], v248 offset:33792
	ds_read_b128 v[184:187], v248 offset:35840
	s_setprio 0
	s_barrier
	s_add_u32 s68, s44, 0x80000
	s_addc_u32 s69, s45, 0
	s_add_i32 s67, s70, s54
	v_lshl_add_u64 v[246:247], s[68:69], 0, v[136:137]
	s_mov_b32 m0, s67
	s_nop 0
	global_load_lds_dwordx4 v[246:247], off
	v_lshl_add_u64 v[246:247], s[68:69], 0, v[132:133]
	s_add_i32 m0, s67, 0x2000
	s_nop 0
	global_load_lds_dwordx4 v[246:247], off
	s_waitcnt vmcnt(6)
	s_barrier
	s_setprio 1
	v_mfma_f32_16x16x32_bf16 v[48:51], v[224:227], v[188:191], v[48:51]
	v_mfma_f32_16x16x32_bf16 v[44:47], v[232:235], v[188:191], v[44:47]
	v_mfma_f32_16x16x32_bf16 v[32:35], v[224:227], v[196:199], v[32:35]
	ds_read_b128 v[188:191], v154 offset:32768
	v_mfma_f32_16x16x32_bf16 v[28:31], v[232:235], v[196:199], v[28:31]
	v_mfma_f32_16x16x32_bf16 v[16:19], v[224:227], v[208:211], v[16:19]
	ds_read_b128 v[196:199], v154 offset:34816
	v_mfma_f32_16x16x32_bf16 v[12:15], v[232:235], v[208:211], v[12:15]
	v_mfma_f32_16x16x32_bf16 v[8:11], v[224:227], v[216:219], v[8:11]
	ds_read_b128 v[208:211], v154 offset:36864
	v_mfma_f32_16x16x32_bf16 v[4:7], v[232:235], v[216:219], v[4:7]
	v_mfma_f32_16x16x32_bf16 v[48:51], v[228:231], v[192:195], v[48:51]
	ds_read_b128 v[216:219], v154 offset:38912
	v_mfma_f32_16x16x32_bf16 v[44:47], v[236:239], v[192:195], v[44:47]
	v_mfma_f32_16x16x32_bf16 v[32:35], v[228:231], v[200:203], v[32:35]
	ds_read_b128 v[192:195], v154 offset:33792
	v_mfma_f32_16x16x32_bf16 v[28:31], v[236:239], v[200:203], v[28:31]
	v_mfma_f32_16x16x32_bf16 v[16:19], v[228:231], v[212:215], v[16:19]
	ds_read_b128 v[200:203], v154 offset:35840
	v_mfma_f32_16x16x32_bf16 v[12:15], v[236:239], v[212:215], v[12:15]
	v_mfma_f32_16x16x32_bf16 v[8:11], v[228:231], v[220:223], v[8:11]
	ds_read_b128 v[212:215], v154 offset:37888
	v_mfma_f32_16x16x32_bf16 v[4:7], v[236:239], v[220:223], v[4:7]
	ds_read_b128 v[220:223], v154 offset:39936
	s_setprio 0
	s_add_i32 s67, 0, 0x18000
	s_barrier
; #define PG8_STAGE(bufoff, gbase, voff) do { _Pragma("unroll") for (int _i = 0; _i < 2; ++_i) \
;     __builtin_amdgcn_global_load_lds((const unsigned*)((const char*)(gbase) + (voff)[_i]), (LAS unsigned*)(lds + (bufoff) + ldsw + _i * 8192), 16, 0, 0); } while (0)
; #define PG8_LDA(dst, b, h) do { _Pragma("unroll") for (int m = 0; m < 4; ++m) _Pragma("unroll") for (int k = 0; k < 2; ++k) dst[m][k] = *(const LAS bf16x8*)(lds + PG8_SA(b, h) + aoff + m * 2048 + k * 1024); } while (0)
; #define PG8_LDB(dst, b, h) do { _Pragma("unroll") for (int n = 0; n < 2; ++n) _Pragma("unroll") for (int k = 0; k < 2; ++k) dst[n][k] = *(const LAS bf16x8*)(lds + PG8_SB(b, h) + boff + n * 2048 + k * 1024); } while (0)
; #define PG8_MMA(ai, bj, At, Bt) do { __builtin_amdgcn_s_setprio(1); _Pragma("unroll") for (int m = 0; m < 4; ++m) _Pragma("unroll") for (int n = 0; n < 2; ++n) _Pragma("unroll") for (int k = 0; k < 2; ++k) \
;     acc[ai][bj][m][n] = __builtin_amdgcn_mfma_f32_16x16x32_bf16(Bt[n][k], At[m][k], acc[ai][bj][m][n], 0, 0, 0); __builtin_amdgcn_s_setprio(0); } while (0)
; #define PG8_WAIT_V(n) asm volatile("s_waitcnt vmcnt(" #n ")" ::: "memory")
; #define PG8_WAIT_L(n) asm volatile("s_waitcnt lgkmcnt(" #n ")" ::: "memory")
; #define PG8_BAR __builtin_amdgcn_s_barrier()
; #define PG8_SCHED __builtin_amdgcn_sched_barrier(0)
; template <class Epi>
; DI void gemm_phase(LAS unsigned char* lds, const Gemm g, const Epi& E) {
;     ...
;       PG8_WAIT_L(8); PG8_BAR; PG8_WAIT_L(0); PG8_MMA(0, 0, At, B0); PG8_BAR; PG8_SCHED;
;       PG8_LDB(B1, 1, 1); PG8_STAGE(PG8_SB(1, 0), b3, voffB);
;       PG8_BAR; PG8_WAIT_L(0); PG8_MMA(0, 1, At, B1); PG8_BAR;
;       PG8_LDA(At, 1, 1); PG8_STAGE(PG8_SA(1, 0), a3, voffA);
;       PG8_BAR; PG8_WAIT_L(0); PG8_MMA(1, 0, At, B0); PG8_BAR; PG8_SCHED;
;       PG8_STAGE(PG8_SB(1, 1), b3 + hstepB, voffB);
;       PG8_WAIT_V(6); PG8_BAR; PG8_MMA(1, 1, At, B1); PG8_BAR;
	s_add_u32 s46, s46, 0x80000
	s_addc_u32 s47, s47, 0
	s_mov_b32 m0, s57
	v_lshl_add_u64 v[224:225], s[46:47], 0, v[138:139]
	global_load_lds_dwordx4 v[224:225], off
	v_lshl_add_u64 v[224:225], s[46:47], 0, v[134:135]
	s_mov_b32 m0, s58
	s_nop 0
	global_load_lds_dwordx4 v[224:225], off
	s_waitcnt lgkmcnt(0)
	s_barrier
	s_waitcnt lgkmcnt(0)
	s_setprio 1
	s_waitcnt lgkmcnt(0)
	v_mfma_f32_16x16x32_bf16 v[128:131], v[156:159], v[188:191], v[128:131]
	v_mfma_f32_16x16x32_bf16 v[124:127], v[180:183], v[188:191], v[124:127]
	v_mfma_f32_16x16x32_bf16 v[120:123], v[156:159], v[196:199], v[120:123]
	v_mfma_f32_16x16x32_bf16 v[116:119], v[180:183], v[196:199], v[116:119]
	v_mfma_f32_16x16x32_bf16 v[104:107], v[156:159], v[208:211], v[104:107]
	v_mfma_f32_16x16x32_bf16 v[100:103], v[180:183], v[208:211], v[100:103]
	v_mfma_f32_16x16x32_bf16 v[88:91], v[156:159], v[216:219], v[88:91]
	v_mfma_f32_16x16x32_bf16 v[84:87], v[180:183], v[216:219], v[84:87]
	v_mfma_f32_16x16x32_bf16 v[128:131], v[160:163], v[192:195], v[128:131]
	v_mfma_f32_16x16x32_bf16 v[124:127], v[184:187], v[192:195], v[124:127]
	v_mfma_f32_16x16x32_bf16 v[120:123], v[160:163], v[200:203], v[120:123]
	v_mfma_f32_16x16x32_bf16 v[116:119], v[184:187], v[200:203], v[116:119]
	v_mfma_f32_16x16x32_bf16 v[104:107], v[160:163], v[212:215], v[104:107]
	v_mfma_f32_16x16x32_bf16 v[100:103], v[184:187], v[212:215], v[100:103]
	v_mfma_f32_16x16x32_bf16 v[88:91], v[160:163], v[220:223], v[88:91]
	v_mfma_f32_16x16x32_bf16 v[84:87], v[184:187], v[220:223], v[84:87]
	s_setprio 0
	s_barrier
	s_add_i32 s46, 0, 0x1c000
	s_add_i32 s47, s67, s54
	v_lshl_add_u64 v[148:149], v[148:149], 0, s[84:85]
	s_mov_b32 m0, s47
	ds_read_b128 v[224:227], v248 offset:49152
	ds_read_b128 v[228:231], v248 offset:50176
	ds_read_b128 v[232:235], v248 offset:51200
	ds_read_b128 v[236:239], v248 offset:52224
	global_load_lds_dwordx4 v[148:149], off
	v_lshl_add_u64 v[148:149], v[240:241], 0, s[84:85]
	s_add_i32 m0, s47, 0x2000
	s_nop 0
	global_load_lds_dwordx4 v[148:149], off
	s_waitcnt vmcnt(8)
	s_barrier
	s_waitcnt lgkmcnt(0)
	s_setprio 1
	s_waitcnt lgkmcnt(0)
	v_mfma_f32_16x16x32_bf16 v[112:115], v[224:227], v[188:191], v[112:115]
	v_mfma_f32_16x16x32_bf16 v[108:111], v[232:235], v[188:191], v[108:111]
	v_mfma_f32_16x16x32_bf16 v[96:99], v[224:227], v[196:199], v[96:99]
	ds_read_b128 v[188:191], v154 offset:49152
	v_mfma_f32_16x16x32_bf16 v[92:95], v[232:235], v[196:199], v[92:95]
	v_mfma_f32_16x16x32_bf16 v[80:83], v[224:227], v[208:211], v[80:83]
	ds_read_b128 v[196:199], v154 offset:51200
	v_mfma_f32_16x16x32_bf16 v[76:79], v[232:235], v[208:211], v[76:79]
	v_mfma_f32_16x16x32_bf16 v[72:75], v[224:227], v[216:219], v[72:75]
	ds_read_b128 v[208:211], v154 offset:53248
	v_mfma_f32_16x16x32_bf16 v[68:71], v[232:235], v[216:219], v[68:71]
	v_mfma_f32_16x16x32_bf16 v[112:115], v[228:231], v[192:195], v[112:115]
	ds_read_b128 v[216:219], v154 offset:55296
	v_mfma_f32_16x16x32_bf16 v[108:111], v[236:239], v[192:195], v[108:111]
	v_mfma_f32_16x16x32_bf16 v[96:99], v[228:231], v[200:203], v[96:99]
	ds_read_b128 v[192:195], v154 offset:50176
	v_mfma_f32_16x16x32_bf16 v[92:95], v[236:239], v[200:203], v[92:95]
	v_mfma_f32_16x16x32_bf16 v[80:83], v[228:231], v[212:215], v[80:83]
	ds_read_b128 v[200:203], v154 offset:52224
	v_mfma_f32_16x16x32_bf16 v[76:79], v[236:239], v[212:215], v[76:79]
	v_mfma_f32_16x16x32_bf16 v[72:75], v[228:231], v[220:223], v[72:75]
	ds_read_b128 v[212:215], v154 offset:54272
	v_mfma_f32_16x16x32_bf16 v[68:71], v[236:239], v[220:223], v[68:71]
	ds_read_b128 v[220:223], v154 offset:56320
	s_setprio 0
	s_mov_b32 m0, s60
	v_lshl_add_u64 v[148:149], v[242:243], 0, s[84:85]
	s_barrier
	global_load_lds_dwordx4 v[148:149], off
	v_lshl_add_u64 v[148:149], v[244:245], 0, s[84:85]
	s_mov_b32 m0, s61
	s_nop 0
	global_load_lds_dwordx4 v[148:149], off
	s_waitcnt vmcnt(8)
	s_barrier
	s_waitcnt lgkmcnt(0)
	s_setprio 1
	s_waitcnt lgkmcnt(0)
	v_mfma_f32_16x16x32_bf16 v[64:67], v[156:159], v[188:191], v[64:67]
	v_mfma_f32_16x16x32_bf16 v[60:63], v[180:183], v[188:191], v[60:63]
	v_mfma_f32_16x16x32_bf16 v[56:59], v[156:159], v[196:199], v[56:59]
	v_mfma_f32_16x16x32_bf16 v[52:55], v[180:183], v[196:199], v[52:55]
	v_mfma_f32_16x16x32_bf16 v[40:43], v[156:159], v[208:211], v[40:43]
	v_mfma_f32_16x16x32_bf16 v[36:39], v[180:183], v[208:211], v[36:39]
	v_mfma_f32_16x16x32_bf16 v[24:27], v[156:159], v[216:219], v[24:27]
	v_mfma_f32_16x16x32_bf16 v[20:23], v[180:183], v[216:219], v[20:23]
	ds_read_b128 v[156:159], v248
	v_mfma_f32_16x16x32_bf16 v[64:67], v[160:163], v[192:195], v[64:67]
	ds_read_b128 v[180:183], v248 offset:2048
	v_mfma_f32_16x16x32_bf16 v[60:63], v[184:187], v[192:195], v[60:63]
	v_mfma_f32_16x16x32_bf16 v[56:59], v[160:163], v[200:203], v[56:59]
	v_mfma_f32_16x16x32_bf16 v[52:55], v[184:187], v[200:203], v[52:55]
	v_mfma_f32_16x16x32_bf16 v[40:43], v[160:163], v[212:215], v[40:43]
	v_mfma_f32_16x16x32_bf16 v[36:39], v[184:187], v[212:215], v[36:39]
	v_mfma_f32_16x16x32_bf16 v[24:27], v[160:163], v[220:223], v[24:27]
	v_mfma_f32_16x16x32_bf16 v[20:23], v[184:187], v[220:223], v[20:23]
	ds_read_b128 v[160:163], v248 offset:1024
	ds_read_b128 v[184:187], v248 offset:3072
	s_setprio 0
	s_barrier
; #define PG8_BAR __builtin_amdgcn_s_barrier()
; template <class Epi>
; DI void gemm_phase(LAS unsigned char* lds, const Gemm g, const Epi& E) {
;     ...
;       PG8_STAGE(PG8_SB(1, 1), b3 + hstepB, voffB);
;       PG8_WAIT_V(6); PG8_BAR; PG8_MMA(1, 1, At, B1); PG8_BAR;
;     }
;   DI void operator()(const f32x4 (&acc)[2][2][4][2], const Unit& u, int wr, int wc, int fr, int fq) const {
;     ...
;     if (pn < 8 || (pn >= 16 && pn < 24)) {
;       bf16_t* base; int ldc, colt;
;       if (pn < 4) { base = Q; ldc = GK; colt = pn * BM; } else if (pn < 8) { base = Kk; ldc = GK; colt = (pn - 4) * BM; } else { base = R; ldc = GV; colt = (pn - 16) * BM; }
;       const int col0 = colt + wc * 32 + 8 * fq;
; #pragma unroll
;       for (int ai = 0; ai < 2; ++ai)
; #pragma unroll
;         for (int m = 0; m < 4; ++m) {
;           bf16_t* rowp = base + (size_t)(row0 + ai * HALF + m * 16) * ldc + col0;
; #pragma unroll
;           for (int bj = 0; bj < 2; ++bj) {
;             const f32x4 v0 = acc[ai][bj][m][0], v1 = acc[ai][bj][m][1];
;             u32x4 w; w.x = cvt_pk_bf16(v0[0], v0[1]); w.y = cvt_pk_bf16(v0[2], v0[3]); w.z = cvt_pk_bf16(v1[0], v1[1]); w.w = cvt_pk_bf16(v1[2], v1[3]);
;             *(u32x4*)(rowp + bj * HALF) = w;
;           }
;         }
;     } else if (pn < 16) {
;       const int e0 = (pn - 8) * BM;
;       const int h = e0 >> 9, el0 = (e0 & 511) + wc * 32 + 8 * fq;
; #pragma unroll
;       for (int ai = 0; ai < 2; ++ai)
; #pragma unroll
;         for (int m = 0; m < 4; ++m) {
;           const int row = row0 + ai * HALF + m * 16;
;           const int b = row >> 14, ch = (row & (SEQ - 1)) >> 6, c = row & 63;
;           bf16_t* tp = VT + ((size_t)((b * 4 + h) * NCH + ch) * HV) * 64 + c;
; #pragma unroll
;           for (int bj = 0; bj < 2; ++bj)
; #pragma unroll
;             for (int n = 0; n < 2; ++n) {
;               const f32x4 v = acc[ai][bj][m][n];
;               const unsigned p0 = cvt_pk_bf16(v[0], v[1]), p1 = cvt_pk_bf16(v[2], v[3]);
;               bf16_t* ep = tp + (size_t)(el0 + bj * HALF + 4 * n) * 64;
;               ep[0] = (bf16_t)(p0 & 0xffffu); ep[64] = (bf16_t)(p0 >> 16); ep[128] = (bf16_t)(p1 & 0xffffu); ep[192] = (bf16_t)(p1 >> 16);
;             }
;         }
;     } else {
;       if (wc == 0) {
; #pragma unroll
;         for (int ai = 0; ai < 2; ++ai)
; #pragma unroll
;           for (int m = 0; m < 4; ++m) {
	s_add_u32 s44, s44, 0x80080
	s_addc_u32 s45, s45, 0
	s_add_i32 s46, s46, s54
	v_lshl_add_u64 v[148:149], s[44:45], 0, v[136:137]
	s_mov_b32 m0, s46
	s_nop 0
	global_load_lds_dwordx4 v[148:149], off
	v_lshl_add_u64 v[148:149], s[44:45], 0, v[132:133]
	s_add_i32 m0, s46, 0x2000
	s_nop 0
	global_load_lds_dwordx4 v[148:149], off
	s_waitcnt vmcnt(6)
	s_barrier
	s_setprio 1
	v_mfma_f32_16x16x32_bf16 v[48:51], v[224:227], v[188:191], v[48:51]
	v_mfma_f32_16x16x32_bf16 v[44:47], v[232:235], v[188:191], v[44:47]
	v_mfma_f32_16x16x32_bf16 v[32:35], v[224:227], v[196:199], v[32:35]
	ds_read_b128 v[188:191], v154
	v_mfma_f32_16x16x32_bf16 v[28:31], v[232:235], v[196:199], v[28:31]
	v_mfma_f32_16x16x32_bf16 v[16:19], v[224:227], v[208:211], v[16:19]
	ds_read_b128 v[196:199], v154 offset:2048
	v_mfma_f32_16x16x32_bf16 v[12:15], v[232:235], v[208:211], v[12:15]
	v_mfma_f32_16x16x32_bf16 v[8:11], v[224:227], v[216:219], v[8:11]
	ds_read_b128 v[208:211], v154 offset:4096
	v_mfma_f32_16x16x32_bf16 v[4:7], v[232:235], v[216:219], v[4:7]
	v_mfma_f32_16x16x32_bf16 v[48:51], v[228:231], v[192:195], v[48:51]
	ds_read_b128 v[216:219], v154 offset:6144
	v_mfma_f32_16x16x32_bf16 v[44:47], v[236:239], v[192:195], v[44:47]
	v_mfma_f32_16x16x32_bf16 v[32:35], v[228:231], v[200:203], v[32:35]
	ds_read_b128 v[192:195], v154 offset:1024
	v_mfma_f32_16x16x32_bf16 v[28:31], v[236:239], v[200:203], v[28:31]
	v_mfma_f32_16x16x32_bf16 v[16:19], v[228:231], v[212:215], v[16:19]
	ds_read_b128 v[200:203], v154 offset:3072
	v_mfma_f32_16x16x32_bf16 v[12:15], v[236:239], v[212:215], v[12:15]
	v_mfma_f32_16x16x32_bf16 v[8:11], v[228:231], v[220:223], v[8:11]
	ds_read_b128 v[212:215], v154 offset:5120
	v_mfma_f32_16x16x32_bf16 v[4:7], v[236:239], v[220:223], v[4:7]
	ds_read_b128 v[220:223], v154 offset:7168
	s_setprio 0
	s_add_i32 s66, s66, 2
	s_add_u32 s42, s42, 0x100
	s_addc_u32 s43, s43, 0
	s_add_u32 s64, s64, 0x100
	s_addc_u32 s65, s65, 0
	s_cmp_gt_u32 s66, 29
	s_barrier
	s_cbranch_scc0 .LBB0_225
	s_waitcnt lgkmcnt(0)
	s_lshl_b32 s23, s40, 8
	s_add_i32 s23, s23, s59
	s_cmp_gt_i32 s62, 7
	s_cselect_b64 s[40:41], -1, 0
	s_and_b32 s27, s62, 0x7ffffff8
	s_cmp_lg_u32 s27, 16
	s_cselect_b64 s[42:43], -1, 0
	s_and_b64 s[44:45], s[40:41], s[42:43]
	v_or_b32_e32 v148, s23, v150
	s_mov_b64 s[42:43], -1
	s_and_b64 vcc, exec, s[44:45]
	s_cbranch_vccz .LBB0_234
	s_cmp_gt_u32 s62, 15
	s_cbranch_scc0 .LBB0_231
	s_andn2_b64 vcc, exec, s[18:19]
	s_cbranch_vccnz .LBB0_230
	v_or_b32_e32 v158, 16, v148
	v_ashrrev_i32_e32 v149, 31, v148
	v_ashrrev_i32_e32 v159, 31, v158
	v_lshlrev_b64 v[156:157], 7, v[148:149]
	v_lshlrev_b64 v[158:159], 7, v[158:159]
	v_lshl_add_u64 v[156:157], v[140:141], 0, v[156:157]
	v_lshl_add_u64 v[158:159], v[140:141], 0, v[158:159]
	global_store_dwordx4 v[156:157], v[128:131], off
	global_store_dwordx4 v[156:157], v[124:127], off offset:16
	global_store_dwordx4 v[158:159], v[120:123], off
	global_store_dwordx4 v[158:159], v[116:119], off offset:16
	v_or_b32_e32 v158, 32, v148
	v_ashrrev_i32_e32 v159, 31, v158
	v_lshlrev_b64 v[158:159], 7, v[158:159]
	v_lshl_add_u64 v[158:159], v[140:141], 0, v[158:159]
	global_store_dwordx4 v[158:159], v[104:107], off
	global_store_dwordx4 v[158:159], v[100:103], off offset:16
	v_or_b32_e32 v158, 48, v148
	v_ashrrev_i32_e32 v159, 31, v158
	v_lshlrev_b64 v[158:159], 7, v[158:159]
	s_movk_i32 s27, 0x4000
	v_lshl_add_u64 v[158:159], v[140:141], 0, v[158:159]
	s_mov_b64 s[42:43], 0x4000
	v_add_co_u32_e32 v160, vcc, s27, v156
	global_store_dwordx4 v[158:159], v[88:91], off
	global_store_dwordx4 v[158:159], v[84:87], off offset:16
	v_lshl_add_u64 v[158:159], v[156:157], 0, s[42:43]
	v_addc_co_u32_e32 v161, vcc, 0, v157, vcc
	s_mov_b64 s[42:43], 0x4800
	global_store_dwordx4 v[160:161], v[64:67], off
	global_store_dwordx4 v[158:159], v[60:63], off offset:16
	v_lshl_add_u64 v[158:159], v[156:157], 0, s[42:43]
	global_store_dwordx4 v[160:161], v[56:59], off offset:2048
	global_store_dwordx4 v[158:159], v[52:55], off offset:16
	s_mov_b64 s[42:43], 0x5000
	v_add_co_u32_e32 v160, vcc, 0x5000, v156
	v_lshl_add_u64 v[158:159], v[156:157], 0, s[42:43]
	s_nop 0
	v_addc_co_u32_e32 v161, vcc, 0, v157, vcc
	s_mov_b64 s[42:43], 0x5800
	global_store_dwordx4 v[160:161], v[40:43], off
	global_store_dwordx4 v[158:159], v[36:39], off offset:16
	v_lshl_add_u64 v[156:157], v[156:157], 0, s[42:43]
	global_store_dwordx4 v[160:161], v[24:27], off offset:2048
	global_store_dwordx4 v[156:157], v[20:23], off offset:16

; #define PG8_STAGE(bufoff, gbase, voff) do { _Pragma("unroll") for (int _i = 0; _i < 2; ++_i) \
;     __builtin_amdgcn_global_load_lds((const unsigned*)((const char*)(gbase) + (voff)[_i]), (LAS unsigned*)(lds + (bufoff) + ldsw + _i * 8192), 16, 0, 0); } while (0)
; #define PG8_LDA(dst, b, h) do { _Pragma("unroll") for (int m = 0; m < 4; ++m) _Pragma("unroll") for (int k = 0; k < 2; ++k) dst[m][k] = *(const LAS bf16x8*)(lds + PG8_SA(b, h) + aoff + m * 2048 + k * 1024); } while (0)
; #define PG8_LDB(dst, b, h) do { _Pragma("unroll") for (int n = 0; n < 2; ++n) _Pragma("unroll") for (int k = 0; k < 2; ++k) dst[n][k] = *(const LAS bf16x8*)(lds + PG8_SB(b, h) + boff + n * 2048 + k * 1024); } while (0)
; #define PG8_MMA(ai, bj, At, Bt) do { __builtin_amdgcn_s_setprio(1); _Pragma("unroll") for (int m = 0; m < 4; ++m) _Pragma("unroll") for (int n = 0; n < 2; ++n) _Pragma("unroll") for (int k = 0; k < 2; ++k) \
;     acc[ai][bj][m][n] = __builtin_amdgcn_mfma_f32_16x16x32_bf16(Bt[n][k], At[m][k], acc[ai][bj][m][n], 0, 0, 0); __builtin_amdgcn_s_setprio(0); } while (0)
; #define PG8_WAIT_L(n) asm volatile("s_waitcnt lgkmcnt(" #n ")" ::: "memory")
; #define PG8_BAR __builtin_amdgcn_s_barrier()
; #define PG8_SCHED __builtin_amdgcn_sched_barrier(0)
; template <class Epi>
; DI void gemm_phase(LAS unsigned char* lds, const Gemm g, const Epi& E) {
;     ...
;     for (int t = 0; t < nt; t += 2) {
;       const bool last = (t == nt - 2);
;       const char* a1 = cA + (size_t)(t + 1) * kstep;
;       const char* a2 = last ? nA : cA + (size_t)(t + 2) * kstep; const char* b2 = last ? nB : cB + (size_t)(t + 2) * kstep;
;       const char* a3 = a2 + kstep; const char* b3 = b2 + kstep;
;       PG8_LDB(B0, 0, 0); PG8_SCHED; PG8_LDA(At, 0, 0); PG8_STAGE(PG8_SA(1, 1), a1 + hstepA, voffA);
;       PG8_WAIT_L(8); PG8_BAR; PG8_WAIT_L(0); PG8_MMA(0, 0, At, B0); PG8_BAR; PG8_SCHED;
;       PG8_LDB(B1, 0, 1); PG8_STAGE(PG8_SB(0, 0), b2, voffB);
;       PG8_BAR; PG8_WAIT_L(0); PG8_MMA(0, 1, At, B1); PG8_BAR;
;     ...
; #pragma unroll
;     for (int a = 0; a < 2; ++a)
; #pragma unroll
;       for (int b = 0; b < 2; ++b)
; #pragma unroll
;         for (int m = 0; m < 4; ++m)
; #pragma unroll
;           for (int n = 0; n < 2; ++n) acc[a][b][m][n] = (f32x4){0.f, 0.f, 0.f, 0.f};
;     cur = nxt; cA = nA; cB = nB; ++ui;
.LBB0_513:
	s_add_u32 s42, s58, 0x80
	s_addc_u32 s43, s59, 0
	s_add_u32 s58, s56, 0x100
	v_mov_b32_e32 v4, 0
	s_addc_u32 s59, s57, 0
	s_mov_b32 s44, 0
	v_mov_b32_e32 v5, v4
	v_mov_b32_e32 v6, v4
	v_mov_b32_e32 v7, v4
	v_mov_b32_e32 v8, v4
	v_mov_b32_e32 v9, v4
	v_mov_b32_e32 v10, v4
	v_mov_b32_e32 v11, v4
	v_mov_b32_e32 v12, v4
	v_mov_b32_e32 v13, v4
	v_mov_b32_e32 v14, v4
	v_mov_b32_e32 v15, v4
	v_mov_b32_e32 v20, v4
	v_mov_b32_e32 v21, v4
	v_mov_b32_e32 v22, v4
	v_mov_b32_e32 v23, v4
	v_mov_b32_e32 v28, v4
	v_mov_b32_e32 v29, v4
	v_mov_b32_e32 v30, v4
	v_mov_b32_e32 v31, v4
	v_mov_b32_e32 v36, v4
	v_mov_b32_e32 v37, v4
	v_mov_b32_e32 v38, v4
	v_mov_b32_e32 v39, v4
	v_mov_b32_e32 v44, v4
	v_mov_b32_e32 v45, v4
	v_mov_b32_e32 v46, v4
	v_mov_b32_e32 v47, v4
	v_mov_b32_e32 v52, v4
	v_mov_b32_e32 v53, v4
	v_mov_b32_e32 v54, v4
	v_mov_b32_e32 v55, v4
	v_mov_b32_e32 v16, v4
	v_mov_b32_e32 v17, v4
	v_mov_b32_e32 v18, v4
	v_mov_b32_e32 v19, v4
	v_mov_b32_e32 v24, v4
	v_mov_b32_e32 v25, v4
	v_mov_b32_e32 v26, v4
	v_mov_b32_e32 v27, v4
	v_mov_b32_e32 v32, v4
	v_mov_b32_e32 v33, v4
	v_mov_b32_e32 v34, v4
	v_mov_b32_e32 v35, v4
	v_mov_b32_e32 v40, v4
	v_mov_b32_e32 v41, v4
	v_mov_b32_e32 v42, v4
	v_mov_b32_e32 v43, v4
	v_mov_b32_e32 v48, v4
	v_mov_b32_e32 v49, v4
	v_mov_b32_e32 v50, v4
	v_mov_b32_e32 v51, v4
	v_mov_b32_e32 v56, v4
	v_mov_b32_e32 v57, v4
	v_mov_b32_e32 v58, v4
	v_mov_b32_e32 v59, v4
	v_mov_b32_e32 v60, v4
	v_mov_b32_e32 v61, v4
	v_mov_b32_e32 v62, v4
	v_mov_b32_e32 v63, v4
	v_mov_b32_e32 v64, v4
	v_mov_b32_e32 v65, v4
	v_mov_b32_e32 v66, v4
	v_mov_b32_e32 v67, v4
	v_mov_b32_e32 v68, v4
	v_mov_b32_e32 v69, v4
	v_mov_b32_e32 v70, v4
	v_mov_b32_e32 v71, v4
	v_mov_b32_e32 v72, v4
	v_mov_b32_e32 v73, v4
	v_mov_b32_e32 v74, v4
	v_mov_b32_e32 v75, v4
	v_mov_b32_e32 v80, v4
	v_mov_b32_e32 v81, v4
	v_mov_b32_e32 v82, v4
	v_mov_b32_e32 v83, v4
	v_mov_b32_e32 v88, v4
	v_mov_b32_e32 v89, v4
	v_mov_b32_e32 v90, v4
	v_mov_b32_e32 v91, v4
	v_mov_b32_e32 v96, v4
	v_mov_b32_e32 v97, v4
	v_mov_b32_e32 v98, v4
	v_mov_b32_e32 v99, v4
	v_mov_b32_e32 v104, v4
	v_mov_b32_e32 v105, v4
	v_mov_b32_e32 v106, v4
	v_mov_b32_e32 v107, v4
	v_mov_b32_e32 v112, v4
	v_mov_b32_e32 v113, v4
	v_mov_b32_e32 v114, v4
	v_mov_b32_e32 v115, v4
	v_mov_b32_e32 v120, v4
	v_mov_b32_e32 v121, v4
	v_mov_b32_e32 v122, v4
	v_mov_b32_e32 v123, v4
	v_mov_b32_e32 v76, v4
	v_mov_b32_e32 v77, v4
	v_mov_b32_e32 v78, v4
	v_mov_b32_e32 v79, v4
	v_mov_b32_e32 v84, v4
	v_mov_b32_e32 v85, v4
	v_mov_b32_e32 v86, v4
	v_mov_b32_e32 v87, v4
	v_mov_b32_e32 v92, v4
	v_mov_b32_e32 v93, v4
	v_mov_b32_e32 v94, v4
	v_mov_b32_e32 v95, v4
	v_mov_b32_e32 v100, v4
	v_mov_b32_e32 v101, v4
	v_mov_b32_e32 v102, v4
	v_mov_b32_e32 v103, v4
	v_mov_b32_e32 v108, v4
	v_mov_b32_e32 v109, v4
	v_mov_b32_e32 v110, v4
	v_mov_b32_e32 v111, v4
	v_mov_b32_e32 v116, v4
	v_mov_b32_e32 v117, v4
	v_mov_b32_e32 v118, v4
	v_mov_b32_e32 v119, v4
	v_mov_b32_e32 v124, v4
	v_mov_b32_e32 v125, v4
	v_mov_b32_e32 v126, v4
	v_mov_b32_e32 v127, v4
	v_mov_b32_e32 v128, v4
	v_mov_b32_e32 v129, v4
	v_mov_b32_e32 v130, v4
	v_mov_b32_e32 v131, v4
	v_add_u32_e32 v248, 0x10000, v193
	ds_read_b128 v[132:135], v248
	ds_read_b128 v[136:139], v248 offset:1024
	ds_read_b128 v[140:143], v248 offset:2048
	ds_read_b128 v[144:147], v248 offset:3072
	ds_read_b128 v[148:151], v195
	ds_read_b128 v[152:155], v195 offset:1024
	ds_read_b128 v[156:159], v195 offset:2048
	ds_read_b128 v[160:163], v195 offset:3072
	ds_read_b128 v[196:199], v195 offset:4096
	ds_read_b128 v[200:203], v195 offset:5120
	ds_read_b128 v[208:211], v195 offset:6144
	ds_read_b128 v[212:215], v195 offset:7168
.LBB0_514:
	s_add_i32 s78, s44, 2
	s_add_u32 s56, s42, 0x80
	s_addc_u32 s45, s43, 0
	s_add_i32 s79, 0, 0x10000
	s_cmp_eq_u32 s72, s44
	s_cselect_b32 s44, s52, s56
	s_cselect_b32 s45, s53, s45
	s_cselect_b32 s57, s55, s59
	s_cselect_b32 s56, s54, s58
	v_lshl_add_u64 v[190:191], s[42:43], 0, v[186:187]
	s_add_i32 m0, s64, 0xc000
	global_load_lds_dwordx4 v[190:191], off
	v_lshl_add_u64 v[190:191], s[42:43], 0, v[188:189]
	s_add_i32 m0, s64, 0xe000
	s_nop 0
	global_load_lds_dwordx4 v[190:191], off
	s_waitcnt lgkmcnt(0)
	s_barrier
	s_waitcnt lgkmcnt(0)
	s_setprio 1
	s_waitcnt lgkmcnt(0)
	v_mfma_f32_16x16x32_bf16 v[128:131], v[132:135], v[148:151], v[128:131]
	v_mfma_f32_16x16x32_bf16 v[124:127], v[140:143], v[148:151], v[124:127]
	v_mfma_f32_16x16x32_bf16 v[116:119], v[132:135], v[156:159], v[116:119]
	v_mfma_f32_16x16x32_bf16 v[108:111], v[140:143], v[156:159], v[108:111]
	v_mfma_f32_16x16x32_bf16 v[100:103], v[132:135], v[196:199], v[100:103]
	v_mfma_f32_16x16x32_bf16 v[92:95], v[140:143], v[196:199], v[92:95]
	v_mfma_f32_16x16x32_bf16 v[84:87], v[132:135], v[208:211], v[84:87]
	v_mfma_f32_16x16x32_bf16 v[76:79], v[140:143], v[208:211], v[76:79]
	v_mfma_f32_16x16x32_bf16 v[128:131], v[136:139], v[152:155], v[128:131]
	v_mfma_f32_16x16x32_bf16 v[124:127], v[144:147], v[152:155], v[124:127]
	v_mfma_f32_16x16x32_bf16 v[116:119], v[136:139], v[160:163], v[116:119]
	v_mfma_f32_16x16x32_bf16 v[108:111], v[144:147], v[160:163], v[108:111]
	v_mfma_f32_16x16x32_bf16 v[100:103], v[136:139], v[200:203], v[100:103]
	v_mfma_f32_16x16x32_bf16 v[92:95], v[144:147], v[200:203], v[92:95]
	v_mfma_f32_16x16x32_bf16 v[84:87], v[136:139], v[212:215], v[84:87]
	v_mfma_f32_16x16x32_bf16 v[76:79], v[144:147], v[212:215], v[76:79]
	s_setprio 0
	s_barrier
	s_add_i32 s80, 0, 0x14000
	s_add_i32 s79, s79, s63
	ds_read_b128 v[216:219], v248 offset:16384
	ds_read_b128 v[220:223], v248 offset:17408
	ds_read_b128 v[224:227], v248 offset:18432
	ds_read_b128 v[228:231], v248 offset:19456
	v_lshl_add_u64 v[190:191], s[56:57], 0, v[2:3]
	s_mov_b32 m0, s79
	v_lshl_add_u64 v[232:233], s[56:57], 0, v[184:185]
	global_load_lds_dwordx4 v[190:191], off
	s_add_i32 m0, s79, 0x2000
	s_nop 0
	global_load_lds_dwordx4 v[232:233], off
	s_waitcnt vmcnt(8)
	s_barrier
; #define PG8_STAGE(bufoff, gbase, voff) do { _Pragma("unroll") for (int _i = 0; _i < 2; ++_i) \
;     __builtin_amdgcn_global_load_lds((const unsigned*)((const char*)(gbase) + (voff)[_i]), (LAS unsigned*)(lds + (bufoff) + ldsw + _i * 8192), 16, 0, 0); } while (0)
; #define PG8_LDA(dst, b, h) do { _Pragma("unroll") for (int m = 0; m < 4; ++m) _Pragma("unroll") for (int k = 0; k < 2; ++k) dst[m][k] = *(const LAS bf16x8*)(lds + PG8_SA(b, h) + aoff + m * 2048 + k * 1024); } while (0)
; #define PG8_LDB(dst, b, h) do { _Pragma("unroll") for (int n = 0; n < 2; ++n) _Pragma("unroll") for (int k = 0; k < 2; ++k) dst[n][k] = *(const LAS bf16x8*)(lds + PG8_SB(b, h) + boff + n * 2048 + k * 1024); } while (0)
; #define PG8_MMA(ai, bj, At, Bt) do { __builtin_amdgcn_s_setprio(1); _Pragma("unroll") for (int m = 0; m < 4; ++m) _Pragma("unroll") for (int n = 0; n < 2; ++n) _Pragma("unroll") for (int k = 0; k < 2; ++k) \
;     acc[ai][bj][m][n] = __builtin_amdgcn_mfma_f32_16x16x32_bf16(Bt[n][k], At[m][k], acc[ai][bj][m][n], 0, 0, 0); __builtin_amdgcn_s_setprio(0); } while (0)
; #define PG8_WAIT_V(n) asm volatile("s_waitcnt vmcnt(" #n ")" ::: "memory")
; #define PG8_WAIT_L(n) asm volatile("s_waitcnt lgkmcnt(" #n ")" ::: "memory")
; #define PG8_BAR __builtin_amdgcn_s_barrier()
; #define PG8_SCHED __builtin_amdgcn_sched_barrier(0)
; template <class Epi>
; DI void gemm_phase(LAS unsigned char* lds, const Gemm g, const Epi& E) {
;     ...
;       PG8_BAR; PG8_WAIT_L(0); PG8_MMA(0, 1, At, B1); PG8_BAR;
;       PG8_LDA(At, 0, 1); PG8_STAGE(PG8_SA(0, 0), a2, voffA);
;       PG8_BAR; PG8_WAIT_L(0); PG8_MMA(1, 0, At, B0); PG8_BAR; PG8_SCHED;
;       PG8_STAGE(PG8_SB(0, 1), b2 + hstepB, voffB);
;       PG8_WAIT_V(6); PG8_BAR; PG8_MMA(1, 1, At, B1); PG8_BAR;
;       PG8_LDB(B0, 1, 0); PG8_SCHED; PG8_LDA(At, 1, 0); PG8_STAGE(PG8_SA(0, 1), a2 + hstepA, voffA);
;       PG8_WAIT_L(8); PG8_BAR; PG8_WAIT_L(0); PG8_MMA(0, 0, At, B0); PG8_BAR; PG8_SCHED;
	s_waitcnt lgkmcnt(0)
	s_setprio 1
	s_waitcnt lgkmcnt(0)
	v_mfma_f32_16x16x32_bf16 v[120:123], v[216:219], v[148:151], v[120:123]
	v_mfma_f32_16x16x32_bf16 v[112:115], v[224:227], v[148:151], v[112:115]
	v_mfma_f32_16x16x32_bf16 v[104:107], v[216:219], v[156:159], v[104:107]
	ds_read_b128 v[148:151], v195 offset:16384
	v_mfma_f32_16x16x32_bf16 v[96:99], v[224:227], v[156:159], v[96:99]
	v_mfma_f32_16x16x32_bf16 v[88:91], v[216:219], v[196:199], v[88:91]
	ds_read_b128 v[156:159], v195 offset:18432
	v_mfma_f32_16x16x32_bf16 v[80:83], v[224:227], v[196:199], v[80:83]
	v_mfma_f32_16x16x32_bf16 v[72:75], v[216:219], v[208:211], v[72:75]
	ds_read_b128 v[196:199], v195 offset:20480
	v_mfma_f32_16x16x32_bf16 v[68:71], v[224:227], v[208:211], v[68:71]
	v_mfma_f32_16x16x32_bf16 v[120:123], v[220:223], v[152:155], v[120:123]
	ds_read_b128 v[208:211], v195 offset:22528
	v_mfma_f32_16x16x32_bf16 v[112:115], v[228:231], v[152:155], v[112:115]
	v_mfma_f32_16x16x32_bf16 v[104:107], v[220:223], v[160:163], v[104:107]
	ds_read_b128 v[152:155], v195 offset:17408
	v_mfma_f32_16x16x32_bf16 v[96:99], v[228:231], v[160:163], v[96:99]
	v_mfma_f32_16x16x32_bf16 v[88:91], v[220:223], v[200:203], v[88:91]
	ds_read_b128 v[160:163], v195 offset:19456
	v_mfma_f32_16x16x32_bf16 v[80:83], v[228:231], v[200:203], v[80:83]
	v_mfma_f32_16x16x32_bf16 v[72:75], v[220:223], v[212:215], v[72:75]
	ds_read_b128 v[200:203], v195 offset:21504
	v_mfma_f32_16x16x32_bf16 v[68:71], v[228:231], v[212:215], v[68:71]
	ds_read_b128 v[212:215], v195 offset:23552
	s_setprio 0
	s_mov_b32 m0, s64
	v_lshl_add_u64 v[234:235], s[44:45], 0, v[180:181]
	s_barrier
	global_load_lds_dwordx4 v[234:235], off
	v_lshl_add_u64 v[236:237], s[44:45], 0, v[182:183]
	s_mov_b32 m0, s65
	s_nop 0
	global_load_lds_dwordx4 v[236:237], off
	s_waitcnt vmcnt(8)
	s_barrier
	s_waitcnt lgkmcnt(0)
	s_setprio 1
	s_waitcnt lgkmcnt(0)
	v_mfma_f32_16x16x32_bf16 v[64:67], v[132:135], v[148:151], v[64:67]
	v_mfma_f32_16x16x32_bf16 v[60:63], v[140:143], v[148:151], v[60:63]
	v_mfma_f32_16x16x32_bf16 v[56:59], v[132:135], v[156:159], v[56:59]
	v_mfma_f32_16x16x32_bf16 v[48:51], v[140:143], v[156:159], v[48:51]
	v_mfma_f32_16x16x32_bf16 v[40:43], v[132:135], v[196:199], v[40:43]
	v_mfma_f32_16x16x32_bf16 v[32:35], v[140:143], v[196:199], v[32:35]
	v_mfma_f32_16x16x32_bf16 v[24:27], v[132:135], v[208:211], v[24:27]
	v_mfma_f32_16x16x32_bf16 v[16:19], v[140:143], v[208:211], v[16:19]
	ds_read_b128 v[132:135], v248 offset:32768
	v_mfma_f32_16x16x32_bf16 v[64:67], v[136:139], v[152:155], v[64:67]
	ds_read_b128 v[140:143], v248 offset:34816
	v_mfma_f32_16x16x32_bf16 v[60:63], v[144:147], v[152:155], v[60:63]
	v_mfma_f32_16x16x32_bf16 v[56:59], v[136:139], v[160:163], v[56:59]
	v_mfma_f32_16x16x32_bf16 v[48:51], v[144:147], v[160:163], v[48:51]
	v_mfma_f32_16x16x32_bf16 v[40:43], v[136:139], v[200:203], v[40:43]
	v_mfma_f32_16x16x32_bf16 v[32:35], v[144:147], v[200:203], v[32:35]
	v_mfma_f32_16x16x32_bf16 v[24:27], v[136:139], v[212:215], v[24:27]
	v_mfma_f32_16x16x32_bf16 v[16:19], v[144:147], v[212:215], v[16:19]
	ds_read_b128 v[136:139], v248 offset:33792
	ds_read_b128 v[144:147], v248 offset:35840
	s_setprio 0
	s_barrier
	s_add_u32 s56, s56, s18
	s_addc_u32 s57, s57, s19
	s_add_i32 s79, s80, s63
	v_lshl_add_u64 v[238:239], s[56:57], 0, v[2:3]
	s_mov_b32 m0, s79
	v_lshl_add_u64 v[240:241], s[56:57], 0, v[184:185]
	global_load_lds_dwordx4 v[238:239], off
	s_add_i32 m0, s79, 0x2000
	s_nop 0
	global_load_lds_dwordx4 v[240:241], off
	s_waitcnt vmcnt(6)
	s_barrier
	s_setprio 1
	v_mfma_f32_16x16x32_bf16 v[52:55], v[216:219], v[148:151], v[52:55]
	v_mfma_f32_16x16x32_bf16 v[44:47], v[224:227], v[148:151], v[44:47]
	v_mfma_f32_16x16x32_bf16 v[36:39], v[216:219], v[156:159], v[36:39]
	ds_read_b128 v[148:151], v195 offset:32768
	v_mfma_f32_16x16x32_bf16 v[28:31], v[224:227], v[156:159], v[28:31]
	v_mfma_f32_16x16x32_bf16 v[20:23], v[216:219], v[196:199], v[20:23]
	ds_read_b128 v[156:159], v195 offset:34816
	v_mfma_f32_16x16x32_bf16 v[12:15], v[224:227], v[196:199], v[12:15]
	v_mfma_f32_16x16x32_bf16 v[8:11], v[216:219], v[208:211], v[8:11]
	ds_read_b128 v[196:199], v195 offset:36864
	v_mfma_f32_16x16x32_bf16 v[4:7], v[224:227], v[208:211], v[4:7]
	v_mfma_f32_16x16x32_bf16 v[52:55], v[220:223], v[152:155], v[52:55]
	ds_read_b128 v[208:211], v195 offset:38912
	v_mfma_f32_16x16x32_bf16 v[44:47], v[228:231], v[152:155], v[44:47]
	v_mfma_f32_16x16x32_bf16 v[36:39], v[220:223], v[160:163], v[36:39]
	ds_read_b128 v[152:155], v195 offset:33792
	v_mfma_f32_16x16x32_bf16 v[28:31], v[228:231], v[160:163], v[28:31]
	v_mfma_f32_16x16x32_bf16 v[20:23], v[220:223], v[200:203], v[20:23]
	ds_read_b128 v[160:163], v195 offset:35840
	v_mfma_f32_16x16x32_bf16 v[12:15], v[228:231], v[200:203], v[12:15]
	v_mfma_f32_16x16x32_bf16 v[8:11], v[220:223], v[212:215], v[8:11]
	ds_read_b128 v[200:203], v195 offset:37888
	v_mfma_f32_16x16x32_bf16 v[4:7], v[228:231], v[212:215], v[4:7]
	ds_read_b128 v[212:215], v195 offset:39936
	s_setprio 0
	s_add_i32 s56, 0, 0x18000
	s_barrier
	s_add_u32 s44, s44, s8
	s_addc_u32 s45, s45, 0
	s_mov_b32 m0, s66
	v_lshl_add_u64 v[216:217], s[44:45], 0, v[180:181]
	global_load_lds_dwordx4 v[216:217], off
	v_lshl_add_u64 v[216:217], s[44:45], 0, v[182:183]
	s_mov_b32 m0, s67
	s_nop 0
	global_load_lds_dwordx4 v[216:217], off
	s_waitcnt lgkmcnt(0)
	s_barrier
; #define PG8_STAGE(bufoff, gbase, voff) do { _Pragma("unroll") for (int _i = 0; _i < 2; ++_i) \
;     __builtin_amdgcn_global_load_lds((const unsigned*)((const char*)(gbase) + (voff)[_i]), (LAS unsigned*)(lds + (bufoff) + ldsw + _i * 8192), 16, 0, 0); } while (0)
; #define PG8_LDA(dst, b, h) do { _Pragma("unroll") for (int m = 0; m < 4; ++m) _Pragma("unroll") for (int k = 0; k < 2; ++k) dst[m][k] = *(const LAS bf16x8*)(lds + PG8_SA(b, h) + aoff + m * 2048 + k * 1024); } while (0)
; #define PG8_LDB(dst, b, h) do { _Pragma("unroll") for (int n = 0; n < 2; ++n) _Pragma("unroll") for (int k = 0; k < 2; ++k) dst[n][k] = *(const LAS bf16x8*)(lds + PG8_SB(b, h) + boff + n * 2048 + k * 1024); } while (0)
; #define PG8_MMA(ai, bj, At, Bt) do { __builtin_amdgcn_s_setprio(1); _Pragma("unroll") for (int m = 0; m < 4; ++m) _Pragma("unroll") for (int n = 0; n < 2; ++n) _Pragma("unroll") for (int k = 0; k < 2; ++k) \
;     acc[ai][bj][m][n] = __builtin_amdgcn_mfma_f32_16x16x32_bf16(Bt[n][k], At[m][k], acc[ai][bj][m][n], 0, 0, 0); __builtin_amdgcn_s_setprio(0); } while (0)
; #define PG8_WAIT_L(n) asm volatile("s_waitcnt lgkmcnt(" #n ")" ::: "memory")
; #define PG8_BAR __builtin_amdgcn_s_barrier()
; #define PG8_SCHED __builtin_amdgcn_sched_barrier(0)
; template <class Epi>
; DI void gemm_phase(LAS unsigned char* lds, const Gemm g, const Epi& E) {
;     ...
;       PG8_WAIT_L(8); PG8_BAR; PG8_WAIT_L(0); PG8_MMA(0, 0, At, B0); PG8_BAR; PG8_SCHED;
;       PG8_LDB(B1, 1, 1); PG8_STAGE(PG8_SB(1, 0), b3, voffB);
;       PG8_BAR; PG8_WAIT_L(0); PG8_MMA(0, 1, At, B1); PG8_BAR;
;       PG8_LDA(At, 1, 1); PG8_STAGE(PG8_SA(1, 0), a3, voffA);
;       PG8_BAR; PG8_WAIT_L(0); PG8_MMA(1, 0, At, B0); PG8_BAR; PG8_SCHED;
	s_waitcnt lgkmcnt(0)
	s_setprio 1
	s_waitcnt lgkmcnt(0)
	v_mfma_f32_16x16x32_bf16 v[128:131], v[132:135], v[148:151], v[128:131]
	v_mfma_f32_16x16x32_bf16 v[124:127], v[140:143], v[148:151], v[124:127]
	v_mfma_f32_16x16x32_bf16 v[116:119], v[132:135], v[156:159], v[116:119]
	v_mfma_f32_16x16x32_bf16 v[108:111], v[140:143], v[156:159], v[108:111]
	v_mfma_f32_16x16x32_bf16 v[100:103], v[132:135], v[196:199], v[100:103]
	v_mfma_f32_16x16x32_bf16 v[92:95], v[140:143], v[196:199], v[92:95]
	v_mfma_f32_16x16x32_bf16 v[84:87], v[132:135], v[208:211], v[84:87]
	v_mfma_f32_16x16x32_bf16 v[76:79], v[140:143], v[208:211], v[76:79]
	v_mfma_f32_16x16x32_bf16 v[128:131], v[136:139], v[152:155], v[128:131]
	v_mfma_f32_16x16x32_bf16 v[124:127], v[144:147], v[152:155], v[124:127]
	v_mfma_f32_16x16x32_bf16 v[116:119], v[136:139], v[160:163], v[116:119]
	v_mfma_f32_16x16x32_bf16 v[108:111], v[144:147], v[160:163], v[108:111]
	v_mfma_f32_16x16x32_bf16 v[100:103], v[136:139], v[200:203], v[100:103]
	v_mfma_f32_16x16x32_bf16 v[92:95], v[144:147], v[200:203], v[92:95]
	v_mfma_f32_16x16x32_bf16 v[84:87], v[136:139], v[212:215], v[84:87]
	v_mfma_f32_16x16x32_bf16 v[76:79], v[144:147], v[212:215], v[76:79]
	s_setprio 0
	s_barrier
	s_add_i32 s44, 0, 0x1c000
	s_add_i32 s45, s56, s63
	v_lshl_add_u64 v[190:191], v[190:191], 0, s[84:85]
	s_mov_b32 m0, s45
	ds_read_b128 v[216:219], v248 offset:49152
	ds_read_b128 v[220:223], v248 offset:50176
	ds_read_b128 v[224:227], v248 offset:51200
	ds_read_b128 v[228:231], v248 offset:52224
	global_load_lds_dwordx4 v[190:191], off
	v_lshl_add_u64 v[190:191], v[232:233], 0, s[84:85]
	s_add_i32 m0, s45, 0x2000
	s_nop 0
	global_load_lds_dwordx4 v[190:191], off
	s_waitcnt vmcnt(8)
	s_barrier
	s_waitcnt lgkmcnt(0)
	s_setprio 1
	s_waitcnt lgkmcnt(0)
	v_mfma_f32_16x16x32_bf16 v[120:123], v[216:219], v[148:151], v[120:123]
	v_mfma_f32_16x16x32_bf16 v[112:115], v[224:227], v[148:151], v[112:115]
	v_mfma_f32_16x16x32_bf16 v[104:107], v[216:219], v[156:159], v[104:107]
	ds_read_b128 v[148:151], v195 offset:49152
	v_mfma_f32_16x16x32_bf16 v[96:99], v[224:227], v[156:159], v[96:99]
	v_mfma_f32_16x16x32_bf16 v[88:91], v[216:219], v[196:199], v[88:91]
	ds_read_b128 v[156:159], v195 offset:51200
	v_mfma_f32_16x16x32_bf16 v[80:83], v[224:227], v[196:199], v[80:83]
	v_mfma_f32_16x16x32_bf16 v[72:75], v[216:219], v[208:211], v[72:75]
	ds_read_b128 v[196:199], v195 offset:53248
	v_mfma_f32_16x16x32_bf16 v[68:71], v[224:227], v[208:211], v[68:71]
	v_mfma_f32_16x16x32_bf16 v[120:123], v[220:223], v[152:155], v[120:123]
	ds_read_b128 v[208:211], v195 offset:55296
	v_mfma_f32_16x16x32_bf16 v[112:115], v[228:231], v[152:155], v[112:115]
	v_mfma_f32_16x16x32_bf16 v[104:107], v[220:223], v[160:163], v[104:107]
	ds_read_b128 v[152:155], v195 offset:50176
	v_mfma_f32_16x16x32_bf16 v[96:99], v[228:231], v[160:163], v[96:99]
	v_mfma_f32_16x16x32_bf16 v[88:91], v[220:223], v[200:203], v[88:91]
	ds_read_b128 v[160:163], v195 offset:52224
	v_mfma_f32_16x16x32_bf16 v[80:83], v[228:231], v[200:203], v[80:83]
	v_mfma_f32_16x16x32_bf16 v[72:75], v[220:223], v[212:215], v[72:75]
	ds_read_b128 v[200:203], v195 offset:54272
	v_mfma_f32_16x16x32_bf16 v[68:71], v[228:231], v[212:215], v[68:71]
	ds_read_b128 v[212:215], v195 offset:56320
	s_setprio 0
	s_mov_b32 m0, s69
	v_lshl_add_u64 v[190:191], v[234:235], 0, s[84:85]
	s_barrier
	global_load_lds_dwordx4 v[190:191], off
	v_lshl_add_u64 v[190:191], v[236:237], 0, s[84:85]
	s_mov_b32 m0, s71
	s_nop 0
	global_load_lds_dwordx4 v[190:191], off
	s_waitcnt vmcnt(8)
	s_barrier
; #define PG8_STAGE(bufoff, gbase, voff) do { _Pragma("unroll") for (int _i = 0; _i < 2; ++_i) \
;     __builtin_amdgcn_global_load_lds((const unsigned*)((const char*)(gbase) + (voff)[_i]), (LAS unsigned*)(lds + (bufoff) + ldsw + _i * 8192), 16, 0, 0); } while (0)
; #define PG8_LDA(dst, b, h) do { _Pragma("unroll") for (int m = 0; m < 4; ++m) _Pragma("unroll") for (int k = 0; k < 2; ++k) dst[m][k] = *(const LAS bf16x8*)(lds + PG8_SA(b, h) + aoff + m * 2048 + k * 1024); } while (0)
; #define PG8_MMA(ai, bj, At, Bt) do { __builtin_amdgcn_s_setprio(1); _Pragma("unroll") for (int m = 0; m < 4; ++m) _Pragma("unroll") for (int n = 0; n < 2; ++n) _Pragma("unroll") for (int k = 0; k < 2; ++k) \
;     acc[ai][bj][m][n] = __builtin_amdgcn_mfma_f32_16x16x32_bf16(Bt[n][k], At[m][k], acc[ai][bj][m][n], 0, 0, 0); __builtin_amdgcn_s_setprio(0); } while (0)
; #define PG8_WAIT_V(n) asm volatile("s_waitcnt vmcnt(" #n ")" ::: "memory")
; #define PG8_WAIT_L(n) asm volatile("s_waitcnt lgkmcnt(" #n ")" ::: "memory")
; #define PG8_BAR __builtin_amdgcn_s_barrier()
; #define PG8_SCHED __builtin_amdgcn_sched_barrier(0)
; template <class Epi>
; DI void gemm_phase(LAS unsigned char* lds, const Gemm g, const Epi& E) {
;     ...
;       PG8_LDA(At, 1, 1); PG8_STAGE(PG8_SA(1, 0), a3, voffA);
;       PG8_BAR; PG8_WAIT_L(0); PG8_MMA(1, 0, At, B0); PG8_BAR; PG8_SCHED;
;       PG8_STAGE(PG8_SB(1, 1), b3 + hstepB, voffB);
;       PG8_WAIT_V(6); PG8_BAR; PG8_MMA(1, 1, At, B1); PG8_BAR;
;     }
;   DI void operator()(const f32x4 (&acc)[2][2][4][2], const Unit& u, int wr, int wc, int fr, int fq) const {
;     ...
;     f32x4 bv[2][2], sv[2][2];
; #pragma unroll
;     for (int bj = 0; bj < 2; ++bj)
; #pragma unroll
;       for (int n = 0; n < 2; ++n) {
;         bv[bj][n] = bias ? *(const f32x4*)(bias + col0 + bj * HALF + 4 * n) : (f32x4){0.f, 0.f, 0.f, 0.f};
;         sv[bj][n] = scale ? *(const f32x4*)(scale + col0 + bj * HALF + 4 * n) : (f32x4){1.f, 1.f, 1.f, 1.f};
	s_waitcnt lgkmcnt(0)
	s_setprio 1
	s_waitcnt lgkmcnt(0)
	v_mfma_f32_16x16x32_bf16 v[64:67], v[132:135], v[148:151], v[64:67]
	v_mfma_f32_16x16x32_bf16 v[60:63], v[140:143], v[148:151], v[60:63]
	v_mfma_f32_16x16x32_bf16 v[56:59], v[132:135], v[156:159], v[56:59]
	v_mfma_f32_16x16x32_bf16 v[48:51], v[140:143], v[156:159], v[48:51]
	v_mfma_f32_16x16x32_bf16 v[40:43], v[132:135], v[196:199], v[40:43]
	v_mfma_f32_16x16x32_bf16 v[32:35], v[140:143], v[196:199], v[32:35]
	v_mfma_f32_16x16x32_bf16 v[24:27], v[132:135], v[208:211], v[24:27]
	v_mfma_f32_16x16x32_bf16 v[16:19], v[140:143], v[208:211], v[16:19]
	ds_read_b128 v[132:135], v248
	v_mfma_f32_16x16x32_bf16 v[64:67], v[136:139], v[152:155], v[64:67]
	ds_read_b128 v[140:143], v248 offset:2048
	v_mfma_f32_16x16x32_bf16 v[60:63], v[144:147], v[152:155], v[60:63]
	v_mfma_f32_16x16x32_bf16 v[56:59], v[136:139], v[160:163], v[56:59]
	v_mfma_f32_16x16x32_bf16 v[48:51], v[144:147], v[160:163], v[48:51]
	v_mfma_f32_16x16x32_bf16 v[40:43], v[136:139], v[200:203], v[40:43]
	v_mfma_f32_16x16x32_bf16 v[32:35], v[144:147], v[200:203], v[32:35]
	v_mfma_f32_16x16x32_bf16 v[24:27], v[136:139], v[212:215], v[24:27]
	v_mfma_f32_16x16x32_bf16 v[16:19], v[144:147], v[212:215], v[16:19]
	ds_read_b128 v[136:139], v248 offset:1024
	ds_read_b128 v[144:147], v248 offset:3072
	s_setprio 0
	s_barrier
	s_add_i32 s44, s44, s63
	v_lshl_add_u64 v[246:247], v[238:239], 0, s[84:85]
	s_mov_b32 m0, s44
	s_nop 0
	global_load_lds_dwordx4 v[246:247], off
	v_lshl_add_u64 v[246:247], v[240:241], 0, s[84:85]
	s_add_i32 m0, s44, 0x2000
	s_nop 0
	global_load_lds_dwordx4 v[246:247], off
	s_waitcnt vmcnt(6)
	s_barrier
	s_setprio 1
	v_mfma_f32_16x16x32_bf16 v[52:55], v[216:219], v[148:151], v[52:55]
	v_mfma_f32_16x16x32_bf16 v[44:47], v[224:227], v[148:151], v[44:47]
	v_mfma_f32_16x16x32_bf16 v[36:39], v[216:219], v[156:159], v[36:39]
	ds_read_b128 v[148:151], v195
	v_mfma_f32_16x16x32_bf16 v[28:31], v[224:227], v[156:159], v[28:31]
	v_mfma_f32_16x16x32_bf16 v[20:23], v[216:219], v[196:199], v[20:23]
	ds_read_b128 v[156:159], v195 offset:2048
	v_mfma_f32_16x16x32_bf16 v[12:15], v[224:227], v[196:199], v[12:15]
	v_mfma_f32_16x16x32_bf16 v[8:11], v[216:219], v[208:211], v[8:11]
	ds_read_b128 v[196:199], v195 offset:4096
	v_mfma_f32_16x16x32_bf16 v[4:7], v[224:227], v[208:211], v[4:7]
	v_mfma_f32_16x16x32_bf16 v[52:55], v[220:223], v[152:155], v[52:55]
	ds_read_b128 v[208:211], v195 offset:6144
	v_mfma_f32_16x16x32_bf16 v[44:47], v[228:231], v[152:155], v[44:47]
	v_mfma_f32_16x16x32_bf16 v[36:39], v[220:223], v[160:163], v[36:39]
	ds_read_b128 v[152:155], v195 offset:1024
	v_mfma_f32_16x16x32_bf16 v[28:31], v[228:231], v[160:163], v[28:31]
	v_mfma_f32_16x16x32_bf16 v[20:23], v[220:223], v[200:203], v[20:23]
	ds_read_b128 v[160:163], v195 offset:3072
	v_mfma_f32_16x16x32_bf16 v[12:15], v[228:231], v[200:203], v[12:15]
	v_mfma_f32_16x16x32_bf16 v[8:11], v[220:223], v[212:215], v[8:11]
	ds_read_b128 v[200:203], v195 offset:5120
	v_mfma_f32_16x16x32_bf16 v[4:7], v[228:231], v[212:215], v[4:7]
	ds_read_b128 v[212:215], v195 offset:7168
	s_setprio 0
	s_add_u32 s42, s42, 0x100
	s_addc_u32 s43, s43, 0
	s_add_u32 s58, s58, 0x100
	s_addc_u32 s59, s59, 0
	s_cmp_ge_u32 s78, s68
	s_mov_b32 s44, s78
	s_barrier
	s_cbranch_scc0 .LBB0_514
	s_waitcnt lgkmcnt(0)
	v_lshl_or_b32 v190, s77, 8, v194
	v_ashrrev_i32_e32 v191, 31, v190
	v_cndmask_b32_e64 v132, 0, 1, s[36:37]
	v_cmp_ne_u32_e64 s[42:43], 1, v132
	s_andn2_b64 vcc, exec, s[36:37]
	v_lshl_add_u64 v[156:157], v[190:191], 2, s[48:49]
	s_cbranch_vccnz .LBB0_517
	global_load_dwordx4 v[132:135], v[156:157], off
	s_branch .LBB0_518
